# prep_gdn conv phase: row loads of conv items 2-4 and 6-8 issued one item ahead into two spare register banks (software pipelining), vmcnt waits recounted
# speedup vs baseline: 1.0073x; 1.0016x over previous
.Lpg_hb_done:
	s_or_b64 exec, exec, s[6:7]
	v_ashrrev_i32_e32 v41, 31, v40
	v_lshlrev_b64 v[36:37], 13, v[40:41]
	v_lshlrev_b32_e32 v20, 1, v0
	v_lshl_or_b32 v22, v105, 6, v36
	v_lshl_add_u64 v[2:3], s[68:69], 0, v[20:21]
	v_mad_u64_u32 v[2:3], s[4:5], v22, s29, v[2:3]
	v_mad_i32_i24 v3, v37, s29, v3
	v_add_co_u32_e32 v6, vcc, s29, v2
	global_load_ushort v84, v[2:3], off
	s_nop 0
	v_addc_co_u32_e32 v7, vcc, 0, v3, vcc
	global_load_ushort v85, v[6:7], off
	v_add_co_u32_e32 v6, vcc, s30, v2
	s_mov_b32 s2, 0x12000
	s_nop 0
	v_addc_co_u32_e32 v7, vcc, 0, v3, vcc
	global_load_ushort v99, v[6:7], off
	v_add_co_u32_e32 v6, vcc, s2, v2
	s_mov_b32 s2, 0x18000
	s_nop 0
	v_addc_co_u32_e32 v7, vcc, 0, v3, vcc
	global_load_ushort v104, v[6:7], off
	v_add_co_u32_e32 v6, vcc, s2, v2
	s_mov_b32 s2, 0x84000
	s_nop 0
	v_addc_co_u32_e32 v7, vcc, 0, v3, vcc
	global_load_ushort v91, v[6:7], off
	v_add_co_u32_e32 v6, vcc, s35, v2
	v_readlane_b32 s36, v250, 3
	s_nop 0
	v_addc_co_u32_e32 v7, vcc, 0, v3, vcc
	global_load_ushort v101, v[6:7], off
	v_add_co_u32_e32 v6, vcc, s60, v2
	v_mov_b32_e32 v1, v21
	s_nop 0
	v_addc_co_u32_e32 v7, vcc, 0, v3, vcc
	global_load_ushort v88, v[6:7], off
	v_add_co_u32_e32 v6, vcc, s61, v2
	v_readlane_b32 s48, v250, 15
	s_nop 0
	v_addc_co_u32_e32 v7, vcc, 0, v3, vcc
	global_load_ushort v93, v[6:7], off
	v_add_co_u32_e32 v6, vcc, s66, v2
	v_readlane_b32 s49, v250, 16
	s_nop 0
	v_addc_co_u32_e32 v7, vcc, 0, v3, vcc
	global_load_ushort v96, v[6:7], off
	v_add_co_u32_e32 v6, vcc, s67, v2
	v_lshl_add_u64 v[0:1], v[0:1], 2, s[48:49]
	s_nop 0
	v_addc_co_u32_e32 v7, vcc, 0, v3, vcc
	global_load_ushort v97, v[6:7], off
	v_add_co_u32_e32 v6, vcc, s64, v2
	v_lshlrev_b32_e32 v20, 2, v5
	s_nop 0
	v_addc_co_u32_e32 v7, vcc, 0, v3, vcc
	global_load_ushort v83, v[6:7], off
	v_add_co_u32_e32 v6, vcc, s65, v2
	global_load_dword v28, v[0:1], off
	s_nop 0
	v_addc_co_u32_e32 v7, vcc, 0, v3, vcc
	global_load_ushort v89, v[6:7], off
	v_add_co_u32_e32 v6, vcc, s74, v2
	v_lshl_add_u64 v[0:1], s[48:49], 0, v[20:21]
	s_nop 0
	v_addc_co_u32_e32 v7, vcc, 0, v3, vcc
	global_load_ushort v78, v[6:7], off
	v_add_co_u32_e32 v6, vcc, s75, v2
	v_lshlrev_b32_e32 v27, 7, v4
	s_nop 0
	v_addc_co_u32_e32 v7, vcc, 0, v3, vcc
	global_load_ushort v81, v[6:7], off
	v_add_co_u32_e32 v6, vcc, s59, v2
	v_readlane_b32 s37, v250, 4
	s_nop 0
	v_addc_co_u32_e32 v7, vcc, 0, v3, vcc
	global_load_ushort v70, v[6:7], off
	v_add_co_u32_e32 v6, vcc, s22, v2
	v_readlane_b32 s38, v250, 5
	s_nop 0
	v_addc_co_u32_e32 v7, vcc, 0, v3, vcc
	global_load_ushort v73, v[6:7], off
	v_add_co_u32_e32 v6, vcc, s23, v2
	v_readlane_b32 s39, v250, 6
	s_nop 0
	v_addc_co_u32_e32 v7, vcc, 0, v3, vcc
	global_load_ushort v75, v[6:7], off
	v_add_co_u32_e32 v6, vcc, s12, v2
	v_readlane_b32 s40, v250, 7
	s_nop 0
	v_addc_co_u32_e32 v7, vcc, 0, v3, vcc
	global_load_ushort v79, v[6:7], off
	v_add_co_u32_e32 v6, vcc, s13, v2
	v_readlane_b32 s41, v250, 8
	s_nop 0
	v_addc_co_u32_e32 v7, vcc, 0, v3, vcc
	global_load_ushort v67, v[6:7], off
	v_add_co_u32_e32 v6, vcc, s28, v2
	v_readlane_b32 s42, v250, 9
	s_nop 0
	v_addc_co_u32_e32 v7, vcc, 0, v3, vcc
	global_load_ushort v71, v[6:7], off
	v_add_co_u32_e32 v6, vcc, s52, v2
	v_readlane_b32 s43, v250, 10
	s_nop 0
	v_addc_co_u32_e32 v7, vcc, 0, v3, vcc
	global_load_ushort v50, v[6:7], off
	v_add_co_u32_e32 v6, vcc, s53, v2
	v_readlane_b32 s44, v250, 11
	s_nop 0
	v_addc_co_u32_e32 v7, vcc, 0, v3, vcc
	global_load_ushort v65, v[6:7], off
	v_add_co_u32_e32 v6, vcc, s2, v2
	s_mov_b32 s2, 0x8a000
	s_nop 0
	v_addc_co_u32_e32 v7, vcc, 0, v3, vcc
	global_load_ushort v41, v[6:7], off
	v_add_co_u32_e32 v6, vcc, s2, v2
	s_mov_b32 s2, 0x90000
	s_nop 0
	v_addc_co_u32_e32 v7, vcc, 0, v3, vcc
	global_load_ushort v51, v[6:7], off
	v_add_co_u32_e32 v6, vcc, s2, v2
	s_mov_b32 s2, 0x96000
	s_nop 0
	v_addc_co_u32_e32 v7, vcc, 0, v3, vcc
	global_load_ushort v59, v[6:7], off
	v_add_co_u32_e32 v6, vcc, s2, v2
	s_mov_b32 s2, 0x9c000
	s_nop 0
	v_addc_co_u32_e32 v7, vcc, 0, v3, vcc
	global_load_ushort v63, v[6:7], off
	v_add_co_u32_e32 v6, vcc, s2, v2
	s_mov_b32 s2, 0xa2000
	s_nop 0
	v_addc_co_u32_e32 v7, vcc, 0, v3, vcc
	global_load_ushort v55, v[6:7], off
	v_add_co_u32_e32 v6, vcc, s2, v2
	s_mov_b32 s2, 0xa8000
	s_nop 0
	v_addc_co_u32_e32 v7, vcc, 0, v3, vcc
	global_load_ushort v58, v[6:7], off
	v_add_co_u32_e32 v6, vcc, s2, v2
	s_mov_b32 s2, 0xae000
	s_nop 0
	v_addc_co_u32_e32 v7, vcc, 0, v3, vcc
	global_load_ushort v53, v[6:7], off
	v_add_co_u32_e32 v6, vcc, s2, v2
	s_mov_b32 s2, 0xb4000
	s_nop 0
	v_addc_co_u32_e32 v7, vcc, 0, v3, vcc
	global_load_ushort v57, v[6:7], off
	v_add_co_u32_e32 v6, vcc, s2, v2
	s_mov_b32 s2, 0xba000
	s_nop 0
	v_addc_co_u32_e32 v7, vcc, 0, v3, vcc
	global_load_ushort v52, v[6:7], off
	v_add_co_u32_e32 v6, vcc, s2, v2
	s_mov_b32 s2, 0xc0000
	s_nop 0
	v_addc_co_u32_e32 v7, vcc, 0, v3, vcc
	global_load_ushort v54, v[6:7], off
	v_add_co_u32_e32 v6, vcc, s2, v2
	s_mov_b32 s2, 0xc6000
	s_nop 0
	v_addc_co_u32_e32 v7, vcc, 0, v3, vcc
	global_load_ushort v56, v[6:7], off
	v_add_co_u32_e32 v6, vcc, s2, v2
	s_mov_b32 s2, 0xcc000
	s_nop 0
	v_addc_co_u32_e32 v7, vcc, 0, v3, vcc
	global_load_ushort v62, v[6:7], off
	v_add_co_u32_e32 v6, vcc, s2, v2
	s_mov_b32 s2, 0xd2000
	s_nop 0
	v_addc_co_u32_e32 v7, vcc, 0, v3, vcc
	global_load_ushort v60, v[6:7], off
	v_add_co_u32_e32 v6, vcc, s2, v2
	s_mov_b32 s2, 0xd8000
	s_nop 0
	v_addc_co_u32_e32 v7, vcc, 0, v3, vcc
	global_load_ushort v61, v[6:7], off
	v_add_co_u32_e32 v6, vcc, s2, v2
	s_mov_b32 s2, 0xde000
	s_nop 0
	v_addc_co_u32_e32 v7, vcc, 0, v3, vcc
	global_load_ushort v64, v[6:7], off
	v_add_co_u32_e32 v6, vcc, s2, v2
	s_mov_b32 s2, 0xe4000
	s_nop 0
	v_addc_co_u32_e32 v7, vcc, 0, v3, vcc
	global_load_ushort v66, v[6:7], off
	v_add_co_u32_e32 v6, vcc, s2, v2
	s_mov_b32 s2, 0xea000
	s_nop 0
	v_addc_co_u32_e32 v7, vcc, 0, v3, vcc
	global_load_ushort v68, v[6:7], off
	v_add_co_u32_e32 v6, vcc, s2, v2
	s_mov_b32 s2, 0xf0000
	s_nop 0
	v_addc_co_u32_e32 v7, vcc, 0, v3, vcc
	global_load_ushort v69, v[6:7], off
	v_add_co_u32_e32 v6, vcc, s2, v2
	s_mov_b32 s2, 0xf6000
	s_nop 0
	v_addc_co_u32_e32 v7, vcc, 0, v3, vcc
	global_load_ushort v72, v[6:7], off
	v_add_co_u32_e32 v6, vcc, s2, v2
	s_mov_b32 s2, 0xfc000
	s_nop 0
	v_addc_co_u32_e32 v7, vcc, 0, v3, vcc
	global_load_ushort v74, v[6:7], off
	v_add_co_u32_e32 v6, vcc, s2, v2
	s_mov_b32 s2, 0x102000
	s_nop 0
	v_addc_co_u32_e32 v7, vcc, 0, v3, vcc
	global_load_ushort v76, v[6:7], off
	v_add_co_u32_e32 v6, vcc, s2, v2
	s_mov_b32 s2, 0x108000
	s_nop 0
	v_addc_co_u32_e32 v7, vcc, 0, v3, vcc
	global_load_ushort v77, v[6:7], off
	v_add_co_u32_e32 v6, vcc, s2, v2
	s_mov_b32 s2, 0x10e000
	s_nop 0
	v_addc_co_u32_e32 v7, vcc, 0, v3, vcc
	global_load_ushort v80, v[6:7], off
	v_add_co_u32_e32 v6, vcc, s2, v2
	s_mov_b32 s2, 0x114000
	s_nop 0
	v_addc_co_u32_e32 v7, vcc, 0, v3, vcc
	global_load_ushort v82, v[6:7], off
	v_add_co_u32_e32 v6, vcc, s2, v2
	s_mov_b32 s2, 0x11a000
	s_nop 0
	v_addc_co_u32_e32 v7, vcc, 0, v3, vcc
	global_load_ushort v86, v[6:7], off
	v_add_co_u32_e32 v6, vcc, s2, v2
	s_mov_b32 s2, 0x120000
	s_nop 0
	v_addc_co_u32_e32 v7, vcc, 0, v3, vcc
	global_load_ushort v87, v[6:7], off
	v_add_co_u32_e32 v6, vcc, s2, v2
	s_mov_b32 s2, 0x126000
	s_nop 0
	v_addc_co_u32_e32 v7, vcc, 0, v3, vcc
	global_load_ushort v90, v[6:7], off
	v_add_co_u32_e32 v6, vcc, s2, v2
	s_mov_b32 s2, 0x12c000
	s_nop 0
	v_addc_co_u32_e32 v7, vcc, 0, v3, vcc
	global_load_ushort v92, v[6:7], off
	v_add_co_u32_e32 v6, vcc, s2, v2
	s_mov_b32 s2, 0x132000
	s_nop 0
	v_addc_co_u32_e32 v7, vcc, 0, v3, vcc
	global_load_ushort v94, v[6:7], off
	v_add_co_u32_e32 v6, vcc, s2, v2
	s_mov_b32 s2, 0x138000
	s_nop 0
	v_addc_co_u32_e32 v7, vcc, 0, v3, vcc
	global_load_ushort v95, v[6:7], off
	v_add_co_u32_e32 v6, vcc, s2, v2
	s_mov_b32 s2, 0x13e000
	s_nop 0
	v_addc_co_u32_e32 v7, vcc, 0, v3, vcc
	global_load_ushort v98, v[6:7], off
	v_add_co_u32_e32 v6, vcc, s2, v2
	s_mov_b32 s2, 0x144000
	s_nop 0
	v_addc_co_u32_e32 v7, vcc, 0, v3, vcc
	global_load_ushort v100, v[6:7], off
	v_add_co_u32_e32 v6, vcc, s2, v2
	s_mov_b32 s2, 0x14a000
	s_nop 0
	v_addc_co_u32_e32 v7, vcc, 0, v3, vcc
	global_load_ushort v102, v[6:7], off
	v_add_co_u32_e32 v6, vcc, s2, v2
	s_mov_b32 s2, 0x150000
	s_nop 0
	v_addc_co_u32_e32 v7, vcc, 0, v3, vcc
	global_load_ushort v103, v[6:7], off
	v_add_co_u32_e32 v6, vcc, s2, v2
	s_mov_b32 s2, 0x156000
	s_nop 0
	v_addc_co_u32_e32 v7, vcc, 0, v3, vcc
	global_load_ushort v106, v[6:7], off
	v_add_co_u32_e32 v6, vcc, s2, v2
	s_mov_b32 s2, 0x15c000
	s_nop 0
	v_addc_co_u32_e32 v7, vcc, 0, v3, vcc
	global_load_ushort v116, v[6:7], off
	v_add_co_u32_e32 v6, vcc, s2, v2
	s_mov_b32 s2, 0x162000
	s_nop 0
	v_addc_co_u32_e32 v7, vcc, 0, v3, vcc
	global_load_ushort v142, v[6:7], off
	v_add_co_u32_e32 v6, vcc, s2, v2
	s_mov_b32 s2, 0x168000
	s_nop 0
	v_addc_co_u32_e32 v7, vcc, 0, v3, vcc
	global_load_ushort v143, v[6:7], off
	v_add_co_u32_e32 v6, vcc, s2, v2
	s_mov_b32 s2, 0x16e000
	s_nop 0
	v_addc_co_u32_e32 v7, vcc, 0, v3, vcc
	global_load_ushort v138, v[6:7], off
	v_add_co_u32_e32 v6, vcc, s2, v2
	s_mov_b32 s2, 0x174000
	s_nop 0
	v_addc_co_u32_e32 v7, vcc, 0, v3, vcc
	global_load_ushort v139, v[6:7], off
	v_add_co_u32_e32 v6, vcc, s2, v2
	s_mov_b32 s2, 0x17a000
	s_nop 0
	v_addc_co_u32_e32 v7, vcc, 0, v3, vcc
	v_add_co_u32_e32 v2, vcc, s2, v2
	global_load_ushort v137, v[6:7], off
	s_nop 0
	v_addc_co_u32_e32 v3, vcc, 0, v3, vcc
	global_load_ushort v207, v[2:3], off
	v_add_co_u32_e32 v2, vcc, s30, v0
	s_movk_i32 s2, 0x400
	s_nop 0
	v_addc_co_u32_e32 v3, vcc, 0, v1, vcc
	global_load_dword v29, v[2:3], off
	v_add_co_u32_e32 v2, vcc, 0x14000, v0
	v_readlane_b32 s45, v250, 12
	s_nop 0
	v_addc_co_u32_e32 v3, vcc, 0, v1, vcc
	v_add_co_u32_e32 v0, vcc, 0x1c000, v0
	global_load_dword v30, v[2:3], off
	s_nop 0
	v_addc_co_u32_e32 v1, vcc, 0, v1, vcc
	global_load_dword v31, v[0:1], off
	v_cmp_gt_i32_e32 vcc, s2, v38
	v_readlane_b32 s46, v250, 13
	v_readlane_b32 s47, v250, 14
	v_readlane_b32 s50, v250, 17
	v_readlane_b32 s51, v250, 18
	s_waitcnt vmcnt(63) expcnt(7) lgkmcnt(15)
	s_barrier
	s_waitcnt vmcnt(63)
	v_lshlrev_b32_e32 v251, 2, v38
	ds_write_b32 v251, v252
	ds_write_b32 v251, v253 offset:2048
	v_readlane_b32 s36, v250, 3
	v_readlane_b32 s37, v250, 4
	v_readlane_b32 s38, v250, 5
	v_readlane_b32 s39, v250, 6
	v_readlane_b32 s40, v250, 7
	v_readlane_b32 s41, v250, 8
	v_readlane_b32 s42, v250, 9
	v_readlane_b32 s43, v250, 10
	v_readlane_b32 s44, v250, 11
	v_readlane_b32 s45, v250, 12
	v_readlane_b32 s46, v250, 13
	v_readlane_b32 s47, v250, 14
	v_readlane_b32 s48, v250, 15
	v_readlane_b32 s49, v250, 16
	v_readlane_b32 s50, v250, 17
	v_readlane_b32 s51, v250, 18
	v_sub_u32_e64 v0, v105, 1 clamp
	v_and_b32_e32 v194, 0xff, v38
	v_or_b32_e32 v12, v0, v8
	v_lshlrev_b32_e32 v39, 6, v105
	v_mad_i64_i32 v[16:17], s[4:5], v12, 3, 0
	v_lshrrev_b32_e32 v24, 4, v194
	v_or_b32_e32 v36, v36, v39
	v_cmp_lt_u32_e32 vcc, 47, v194
	v_mov_b64_e32 v[4:5], 0x20600000
	v_mov_b64_e32 v[2:3], 0x5000
	v_add_u32_e32 v18, -3, v24
	v_mov_b32_e32 v6, v24
	v_mov_b64_e32 v[8:9], v[16:17]
	s_waitcnt lgkmcnt(0)
	s_barrier
	s_and_saveexec_b64 s[4:5], vcc
	v_mov_b64_e32 v[4:5], 0x8100000
	v_mov_b64_e32 v[2:3], 0x6000
	v_mov_b32_e32 v6, v18
	v_mov_b64_e32 v[8:9], v[36:37]
	s_or_b64 exec, exec, s[4:5]
	v_lshlrev_b32_e32 v195, 3, v38
	v_and_b32_e32 v25, 0x78, v195
	v_or_b32_e32 v113, v27, v25
	v_lshlrev_b32_e32 v20, 1, v113
	v_lshl_add_u64 v[4:5], s[82:83], 0, v[4:5]
	v_mov_b32_e32 v7, v21
	v_lshl_add_u64 v[4:5], v[4:5], 0, v[20:21]
	v_lshl_add_u64 v[6:7], v[8:9], 0, v[6:7]
	v_mad_u64_u32 v[4:5], s[4:5], v6, v2, v[4:5]
	v_mov_b32_e32 v6, v5
	v_mad_u64_u32 v[2:3], s[4:5], v7, v2, v[6:7]
	v_cmp_lt_u32_e64 s[4:5], 31, v194
	v_lshl_add_u64 v[0:1], s[14:15], 0, v[20:21]
	v_lshl_add_u64 v[48:49], s[68:69], 0, v[20:21]
	v_cndmask_b32_e64 v10, 1, -2, s[4:5]
	v_mov_b32_e32 v5, v2
	v_cndmask_b32_e64 v3, v17, v37, s[4:5]
	v_cndmask_b32_e64 v2, v16, v36, s[4:5]
	v_add_u32_e32 v20, v10, v24
	v_cndmask_b32_e64 v114, v189, v190, s[4:5]
	v_cndmask_b32_e64 v9, v1, v49, s[4:5]
	v_cndmask_b32_e64 v8, v0, v48, s[4:5]
	v_lshl_add_u64 v[46:47], v[2:3], 0, v[20:21]
	v_mul_lo_u32 v20, v47, v114
	v_mad_u64_u32 v[2:3], s[6:7], v46, v114, v[8:9]
	v_add_u32_e32 v3, v20, v3
	global_load_dwordx4 v[4:7], v[4:5], off
	v_cmp_lt_u32_e64 s[6:7], 15, v194
	global_load_dwordx4 v[8:11], v[2:3], off
	v_add_u32_e32 v42, -1, v24
	s_and_saveexec_b64 s[8:9], s[6:7]
	s_xor_b64 s[8:9], exec, s[8:9]
	v_mov_b32_e32 v43, v21
	v_lshl_add_u64 v[0:1], v[36:37], 0, v[42:43]
	v_mad_u64_u32 v[2:3], s[10:11], v0, s29, v[48:49]
	v_mov_b32_e32 v0, v3
	v_mad_u64_u32 v[0:1], s[10:11], v1, s29, v[0:1]
	v_mov_b32_e32 v3, v0
	s_or_saveexec_b64 s[8:9], s[8:9]
	s_mov_b32 s2, 0xf000
	v_mad_i64_i32 v[44:45], s[10:11], v12, s2, 0
	s_xor_b64 exec, exec, s[8:9]
	v_lshl_add_u64 v[0:1], v[0:1], 0, v[44:45]
	s_mov_b64 s[10:11], 0xa000
	v_lshl_add_u64 v[2:3], v[0:1], 0, s[10:11]
	s_or_b64 exec, exec, s[8:9]
	v_or_b32_e32 v115, v36, v24
	global_load_dwordx4 v[12:15], v[2:3], off
	v_mul_lo_u32 v112, v37, s29
	v_mad_u64_u32 v[0:1], s[8:9], v115, s29, v[48:49]
	v_add_u32_e32 v1, v112, v1
	global_load_dwordx4 v[0:3], v[0:1], off
	v_or_b32_e32 v244, 0x100, v194
	v_lshrrev_b32_e32 v245, 4, v244
	v_add_u32_e32 v208, -3, v245
	v_add_u32_e32 v210, -2, v245
	v_or_b32_e32 v208, v36, v208
	v_or_b32_e32 v210, v36, v210
	v_add_u32_e32 v212, -1, v245
	v_mad_u64_u32 v[208:209], s[98:99], v208, s29, v[48:49]
	v_mad_u64_u32 v[210:211], s[98:99], v210, s29, v[48:49]
	v_or_b32_e32 v212, v36, v212
	v_add_u32_e32 v209, v112, v209
	v_add_u32_e32 v211, v112, v211
	v_mad_u64_u32 v[212:213], s[98:99], v212, s29, v[48:49]
	v_or_b32_e32 v220, v36, v245
	global_load_dwordx4 v[216:219], v[208:209], off
	s_nop 0
	global_load_dwordx4 v[208:211], v[210:211], off
	v_add_u32_e32 v213, v112, v213
	v_mad_u64_u32 v[220:221], s[98:99], v220, s29, v[48:49]
	global_load_dwordx4 v[212:215], v[212:213], off
	v_add_u32_e32 v221, v112, v221
	global_load_dwordx4 v[220:223], v[220:221], off
	v_cmp_gt_u32_e64 s[8:9], 32, v194
	v_cmp_gt_u32_e64 s[10:11], 48, v194
	v_or_b32_e32 v26, v105, v24
	s_and_b64 s[24:25], s[8:9], s[0:1]
	s_and_b64 s[10:11], s[10:11], s[0:1]
	v_lshl_add_u32 v108, v25, 2, 0
	v_cmp_eq_u32_e64 s[0:1], 0, v26
	s_waitcnt vmcnt(6)
	v_cndmask_b32_e64 v26, v8, 0, s[24:25]
	v_cndmask_b32_e64 v117, v9, 0, s[24:25]
	v_cndmask_b32_e64 v8, v11, 0, s[24:25]
	v_cndmask_b32_e64 v111, v5, 0, s[10:11]
	v_cndmask_b32_e64 v9, v6, 0, s[10:11]
	v_cndmask_b32_e64 v5, v7, 0, s[10:11]
	ds_read_b128 v[118:121], v108
	ds_read_b128 v[122:125], v108 offset:16
	ds_read_b128 v[128:131], v108 offset:1024
	ds_read_b128 v[132:135], v108 offset:1040
	ds_read_b128 v[144:147], v108 offset:2048
	ds_read_b128 v[148:151], v108 offset:2064
	ds_read_b128 v[152:155], v108 offset:3072
	ds_read_b128 v[156:159], v108 offset:3088
	v_cndmask_b32_e64 v109, v4, 0, s[10:11]
	v_cndmask_b32_e64 v110, v10, 0, s[24:25]
	v_lshlrev_b32_e32 v4, 16, v5
	v_and_b32_e32 v5, 0xffff0000, v5
	v_lshlrev_b32_e32 v6, 16, v8
	v_and_b32_e32 v7, 0xffff0000, v8
	v_lshlrev_b32_e32 v8, 16, v9
	v_and_b32_e32 v9, 0xffff0000, v9
	v_lshlrev_b32_e32 v10, 16, v110
	v_and_b32_e32 v11, 0xffff0000, v110
	v_lshlrev_b32_e32 v110, 16, v111
	v_and_b32_e32 v111, 0xffff0000, v111
	s_waitcnt lgkmcnt(6)
	v_pk_fma_f32 v[4:5], v[124:125], v[4:5], 0 op_sel_hi:[1,1,0]
	v_pk_fma_f32 v[8:9], v[122:123], v[8:9], 0 op_sel_hi:[1,1,0]
	v_lshlrev_b32_e32 v140, 16, v117
	v_and_b32_e32 v141, 0xffff0000, v117
	v_pk_fma_f32 v[110:111], v[120:121], v[110:111], 0 op_sel_hi:[1,1,0]
	s_waitcnt lgkmcnt(4)
	v_pk_fma_f32 v[4:5], v[134:135], v[6:7], v[4:5]
	v_pk_fma_f32 v[6:7], v[132:133], v[10:11], v[8:9]
	v_pk_fma_f32 v[8:9], v[130:131], v[140:141], v[110:111]
	v_or_b32_e32 v197, 0x100, v194
	v_and_b32_e32 v47, 64, v191
	v_lshrrev_b32_e32 v198, 4, v197
	v_xor_b32_e32 v23, 1, v191
	v_add_u32_e32 v43, 64, v47
	v_cmp_lt_i32_e64 s[8:9], v23, v43
	v_mul_i32_i24_e32 v19, 0x10e00, v19
	v_add_u32_e32 v196, 0, v19
	v_cndmask_b32_e64 v23, v191, v23, s[8:9]
	v_lshlrev_b32_e32 v23, 2, v23
	v_mul_u32_u24_e32 v201, 0x110, v24
	v_or_b32_e32 v199, 0x200, v194
	v_lshrrev_b32_e32 v200, 4, v199
	v_mul_u32_u24_e32 v204, 0x110, v198
	v_or_b32_e32 v202, 0x300, v194
	v_lshrrev_b32_e32 v203, 4, v202
	v_mul_u32_u24_e32 v205, 0x110, v200
	v_mul_u32_u24_e32 v206, 0x110, v203
	s_waitcnt vmcnt(5)
	v_cndmask_b32_e64 v11, v15, 0, s[0:1]
	v_cndmask_b32_e64 v110, v13, 0, s[0:1]
	v_cndmask_b32_e64 v13, v14, 0, s[0:1]
	v_lshlrev_b32_e32 v10, 16, v11
	v_and_b32_e32 v11, 0xffff0000, v11
	v_cndmask_b32_e64 v117, v12, 0, s[0:1]
	v_lshlrev_b32_e32 v12, 16, v13
	v_and_b32_e32 v13, 0xffff0000, v13
	v_lshlrev_b32_e32 v14, 16, v110
	v_and_b32_e32 v15, 0xffff0000, v110
	s_waitcnt lgkmcnt(2)
	v_pk_fma_f32 v[4:5], v[150:151], v[10:11], v[4:5]
	s_waitcnt vmcnt(4)
	v_lshlrev_b32_e32 v10, 16, v3
	v_and_b32_e32 v11, 0xffff0000, v3
	v_pk_fma_f32 v[6:7], v[148:149], v[12:13], v[6:7]
	v_pk_fma_f32 v[8:9], v[146:147], v[14:15], v[8:9]
	v_lshlrev_b32_e32 v12, 16, v2
	v_and_b32_e32 v13, 0xffff0000, v2
	v_lshlrev_b32_e32 v2, 16, v1
	v_and_b32_e32 v3, 0xffff0000, v1
	s_waitcnt lgkmcnt(0)
	v_pk_fma_f32 v[4:5], v[158:159], v[10:11], v[4:5]
	v_pk_fma_f32 v[6:7], v[156:157], v[12:13], v[6:7]
	v_pk_fma_f32 v[110:111], v[154:155], v[2:3], v[8:9]
	v_mul_f32_e32 v1, 0xbfb8aa3b, v4
	v_mul_f32_e32 v2, 0xbfb8aa3b, v5
	v_mul_f32_e32 v3, 0xbfb8aa3b, v6
	v_exp_f32_e32 v1, v1
	v_exp_f32_e32 v2, v2
	v_exp_f32_e32 v3, v3
	v_mul_f32_e32 v9, 0xbfb8aa3b, v110
	v_exp_f32_e32 v11, v9
	v_add_f32_e32 v1, 1.0, v1
	v_add_f32_e32 v9, 1.0, v2
	v_add_f32_e32 v12, 1.0, v3
	v_rcp_f32_e32 v2, v1
	v_rcp_f32_e32 v3, v9
	v_mul_f32_e32 v8, 0xbfb8aa3b, v7
	v_exp_f32_e32 v8, v8
	v_mul_f32_e32 v10, 0xbfb8aa3b, v111
	v_pk_mul_f32 v[120:121], v[4:5], v[2:3]
	v_add_f32_e32 v2, 1.0, v11
	v_rcp_f32_e32 v130, v2
	v_lshlrev_b32_e32 v2, 16, v109
	v_and_b32_e32 v3, 0xffff0000, v109
	v_pk_fma_f32 v[2:3], v[118:119], v[2:3], 0 op_sel_hi:[1,1,0]
	v_lshlrev_b32_e32 v4, 16, v26
	v_and_b32_e32 v5, 0xffff0000, v26
	v_pk_fma_f32 v[2:3], v[128:129], v[4:5], v[2:3]
	v_lshlrev_b32_e32 v4, 16, v117
	v_and_b32_e32 v5, 0xffff0000, v117
	v_add_f32_e32 v1, 1.0, v8
	v_pk_fma_f32 v[2:3], v[144:145], v[4:5], v[2:3]
	v_lshlrev_b32_e32 v4, 16, v0
	v_and_b32_e32 v5, 0xffff0000, v0
	v_rcp_f32_e32 v9, v1
	v_exp_f32_e32 v1, v10
	v_pk_fma_f32 v[118:119], v[152:153], v[4:5], v[2:3]
	v_rcp_f32_e32 v8, v12
	v_mul_f32_e32 v0, 0xbfb8aa3b, v118
	v_exp_f32_e32 v26, v0
	v_add_f32_e32 v126, 1.0, v1
	v_pk_mul_f32 v[124:125], v[6:7], v[8:9]
	s_nop 0
	v_add_u32_e32 v226, -3, v200
	v_add_u32_e32 v228, -2, v200
	v_or_b32_e32 v226, v36, v226
	v_or_b32_e32 v228, v36, v228
	v_add_u32_e32 v230, -1, v200
	v_mad_u64_u32 v[226:227], s[98:99], v226, s29, v[48:49]
	v_mad_u64_u32 v[228:229], s[98:99], v228, s29, v[48:49]
	v_or_b32_e32 v230, v36, v230
	v_add_u32_e32 v227, v112, v227
	v_add_u32_e32 v229, v112, v229
	v_mad_u64_u32 v[230:231], s[98:99], v230, s29, v[48:49]
	v_or_b32_e32 v238, v36, v200
	global_load_dwordx4 v[234:237], v[226:227], off
	s_nop 0
	global_load_dwordx4 v[226:229], v[228:229], off
	v_add_u32_e32 v231, v112, v231
	v_mad_u64_u32 v[238:239], s[98:99], v238, s29, v[48:49]
	global_load_dwordx4 v[230:233], v[230:231], off
	v_add_u32_e32 v239, v112, v239
	global_load_dwordx4 v[238:241], v[238:239], off
	v_mul_f32_e32 v109, 0xbfb8aa3b, v119
	v_exp_f32_e32 v109, v109
	v_add_f32_e32 v26, 1.0, v26
	v_rcp_f32_e32 v128, v26
	v_rcp_f32_e32 v131, v126
	v_add_f32_e32 v26, 1.0, v109
	v_rcp_f32_e32 v129, v26
	v_pk_mul_f32 v[132:133], v[124:125], v[124:125]
	v_pk_mul_f32 v[130:131], v[110:111], v[130:131]
	v_pk_mul_f32 v[122:123], v[120:121], v[120:121]
	v_pk_mul_f32 v[118:119], v[118:119], v[128:129]
	v_pk_mul_f32 v[110:111], v[130:131], v[130:131]
	v_pk_mul_f32 v[128:129], v[118:119], v[118:119]
	v_xor_b32_e32 v109, 2, v191
	v_add_f32_e32 v26, v128, v129
	v_add_f32_e32 v26, v110, v26
	v_add_f32_e32 v26, v111, v26
	v_add_f32_e32 v26, v132, v26
	v_add_f32_e32 v26, v133, v26
	v_add_f32_e32 v26, v122, v26
	v_add_f32_e32 v26, v123, v26
	ds_bpermute_b32 v110, v23, v26
	v_cmp_lt_i32_e64 s[8:9], v109, v43
	s_waitcnt lgkmcnt(0)
	v_add_f32_e32 v26, v26, v110
	v_cndmask_b32_e64 v109, v191, v109, s[8:9]
	v_lshlrev_b32_e32 v109, 2, v109
	ds_bpermute_b32 v111, v109, v26
	v_xor_b32_e32 v110, 4, v191
	v_cmp_lt_i32_e64 s[8:9], v110, v43
	s_waitcnt lgkmcnt(0)
	v_add_f32_e32 v26, v26, v111
	v_cndmask_b32_e64 v110, v191, v110, s[8:9]
	v_lshlrev_b32_e32 v110, 2, v110
	ds_bpermute_b32 v117, v110, v26
	v_xor_b32_e32 v111, 8, v191
	v_cmp_lt_i32_e64 s[8:9], v111, v43
	s_waitcnt lgkmcnt(0)
	v_add_f32_e32 v26, v26, v117
	v_cndmask_b32_e64 v43, v191, v111, s[8:9]
	v_lshlrev_b32_e32 v111, 2, v43
	ds_bpermute_b32 v43, v111, v26
	s_waitcnt lgkmcnt(0)
	v_add_f32_e32 v26, v26, v43
	v_add_f32_e32 v26, 0x358637bd, v26
	v_mul_f32_e32 v43, 0x4b800000, v26
	v_cmp_gt_f32_e64 s[8:9], s70, v26
	s_waitcnt vmcnt(7)
	v_lshlrev_b32_e32 v140, 16, v219
	v_cndmask_b32_e64 v26, v26, v43, s[8:9]
	v_rsq_f32_e32 v26, v26
	v_and_b32_e32 v141, 0xffff0000, v219
	v_mul_f32_e32 v19, 0x45800000, v26
	v_cndmask_b32_e64 v19, v26, v19, s[8:9]
	v_mul_f32_e32 v26, 0x3db504f3, v19
	v_pk_mul_f32 v[118:119], v[118:119], v[26:27] op_sel_hi:[1,0]
	v_pk_mul_f32 v[122:123], v[130:131], v[26:27] op_sel_hi:[1,0]
	v_pk_mul_f32 v[124:125], v[124:125], v[26:27] op_sel_hi:[1,0]
	v_pk_mul_f32 v[128:129], v[120:121], v[26:27] op_sel_hi:[1,0]
	v_lshlrev_b32_e32 v26, 1, v25
	v_cvt_pk_bf16_f32 v118, v118, v119
	v_cvt_pk_bf16_f32 v119, v122, v123
	v_cvt_pk_bf16_f32 v120, v124, v125
	v_cvt_pk_bf16_f32 v121, v128, v129
	v_add3_u32 v117, v196, v201, v26
	ds_write_b128 v117, v[118:121] offset:4096
	ds_read_b128 v[118:121], v108 offset:16
	ds_read_b128 v[122:125], v108 offset:1040
	ds_read_b128 v[128:131], v108 offset:2064
	ds_read_b128 v[132:135], v108 offset:3088
	ds_read_b128 v[144:147], v108
	s_waitcnt lgkmcnt(4)
	v_pk_fma_f32 v[120:121], v[120:121], v[140:141], 0 op_sel_hi:[1,1,0]
	s_waitcnt vmcnt(6)
	v_lshlrev_b32_e32 v140, 16, v211
	v_and_b32_e32 v141, 0xffff0000, v211
	s_waitcnt lgkmcnt(3)
	v_pk_fma_f32 v[120:121], v[124:125], v[140:141], v[120:121]
	s_waitcnt vmcnt(5)
	v_lshlrev_b32_e32 v124, 16, v215
	v_and_b32_e32 v125, 0xffff0000, v215
	s_waitcnt lgkmcnt(2)
	v_pk_fma_f32 v[120:121], v[130:131], v[124:125], v[120:121]
	s_waitcnt vmcnt(4)
	v_lshlrev_b32_e32 v124, 16, v223
	v_and_b32_e32 v125, 0xffff0000, v223
	s_waitcnt lgkmcnt(1)
	v_pk_fma_f32 v[120:121], v[134:135], v[124:125], v[120:121]
	ds_read_b128 v[148:151], v108 offset:1024
	ds_read_b128 v[152:155], v108 offset:2048
	ds_read_b128 v[156:159], v108 offset:3072
	v_mul_f32_e32 v3, 0xbfb8aa3b, v120
	v_exp_f32_e32 v3, v3
	v_mul_f32_e32 v7, 0xbfb8aa3b, v121
	v_exp_f32_e32 v7, v7
	v_and_b32_e32 v15, 0xffff0000, v209
	v_add_f32_e32 v3, 1.0, v3
	v_rcp_f32_e32 v124, v3
	v_add_f32_e32 v3, 1.0, v7
	v_rcp_f32_e32 v125, v3
	v_and_b32_e32 v7, 0xffff0000, v222
	v_pk_mul_f32 v[120:121], v[120:121], v[124:125]
	v_lshlrev_b32_e32 v124, 16, v218
	v_and_b32_e32 v125, 0xffff0000, v218
	v_pk_fma_f32 v[10:11], v[118:119], v[124:125], 0 op_sel_hi:[1,1,0]
	v_lshlrev_b32_e32 v118, 16, v210
	v_and_b32_e32 v119, 0xffff0000, v210
	v_pk_fma_f32 v[2:3], v[122:123], v[118:119], v[10:11]
	v_lshlrev_b32_e32 v10, 16, v214
	v_and_b32_e32 v11, 0xffff0000, v214
	v_pk_fma_f32 v[2:3], v[128:129], v[10:11], v[2:3]
	v_lshlrev_b32_e32 v6, 16, v222
	v_pk_fma_f32 v[2:3], v[132:133], v[6:7], v[2:3]
	v_lshlrev_b32_e32 v10, 16, v217
	v_mul_f32_e32 v6, 0xbfb8aa3b, v2
	v_mul_f32_e32 v7, 0xbfb8aa3b, v3
	v_exp_f32_e32 v6, v6
	v_exp_f32_e32 v7, v7
	v_and_b32_e32 v11, 0xffff0000, v217
	s_waitcnt lgkmcnt(3)
	v_pk_fma_f32 v[10:11], v[146:147], v[10:11], 0 op_sel_hi:[1,1,0]
	v_lshlrev_b32_e32 v14, 16, v209
	s_waitcnt lgkmcnt(2)
	v_pk_fma_f32 v[10:11], v[150:151], v[14:15], v[10:11]
	v_lshlrev_b32_e32 v14, 16, v213
	v_and_b32_e32 v15, 0xffff0000, v213
	s_waitcnt lgkmcnt(1)
	v_pk_fma_f32 v[10:11], v[154:155], v[14:15], v[10:11]
	v_lshlrev_b32_e32 v14, 16, v221
	v_and_b32_e32 v15, 0xffff0000, v221
	v_add_f32_e32 v6, 1.0, v6
	v_add_f32_e32 v7, 1.0, v7
	s_waitcnt lgkmcnt(0)
	v_pk_fma_f32 v[122:123], v[158:159], v[14:15], v[10:11]
	v_rcp_f32_e32 v6, v6
	v_rcp_f32_e32 v7, v7
	v_mul_f32_e32 v1, 0xbfb8aa3b, v122
	v_exp_f32_e32 v1, v1
	v_mul_f32_e32 v5, 0xbfb8aa3b, v123
	v_pk_mul_f32 v[124:125], v[2:3], v[6:7]
	v_lshlrev_b32_e32 v2, 16, v216
	v_and_b32_e32 v3, 0xffff0000, v216
	v_add_f32_e32 v1, 1.0, v1
	v_pk_fma_f32 v[2:3], v[144:145], v[2:3], 0 op_sel_hi:[1,1,0]
	v_lshlrev_b32_e32 v6, 16, v208
	v_and_b32_e32 v7, 0xffff0000, v208
	v_rcp_f32_e32 v128, v1
	v_pk_fma_f32 v[0:1], v[148:149], v[6:7], v[2:3]
	v_lshlrev_b32_e32 v2, 16, v212
	v_and_b32_e32 v3, 0xffff0000, v212
	v_exp_f32_e32 v5, v5
	v_pk_fma_f32 v[0:1], v[152:153], v[2:3], v[0:1]
	v_lshlrev_b32_e32 v2, 16, v220
	v_and_b32_e32 v3, 0xffff0000, v220
	v_pk_fma_f32 v[130:131], v[156:157], v[2:3], v[0:1]
	v_add_f32_e32 v19, 1.0, v5
	s_nop 0
	v_add_u32_e32 v208, -3, v203
	v_add_u32_e32 v210, -2, v203
	v_or_b32_e32 v208, v36, v208
	v_or_b32_e32 v210, v36, v210
	v_add_u32_e32 v212, -1, v203
	v_mad_u64_u32 v[208:209], s[98:99], v208, s29, v[48:49]
	v_mad_u64_u32 v[210:211], s[98:99], v210, s29, v[48:49]
	v_or_b32_e32 v212, v36, v212
	v_add_u32_e32 v209, v112, v209
	v_add_u32_e32 v211, v112, v211
	v_mad_u64_u32 v[212:213], s[98:99], v212, s29, v[48:49]
	v_or_b32_e32 v220, v36, v203
	global_load_dwordx4 v[216:219], v[208:209], off
	s_nop 0
	global_load_dwordx4 v[208:211], v[210:211], off
	v_add_u32_e32 v213, v112, v213
	v_mad_u64_u32 v[220:221], s[98:99], v220, s29, v[48:49]
	global_load_dwordx4 v[212:215], v[212:213], off
	v_add_u32_e32 v221, v112, v221
	global_load_dwordx4 v[220:223], v[220:221], off
	v_mul_f32_e32 v25, 0xbfb8aa3b, v130
	v_exp_f32_e32 v25, v25
	v_mul_f32_e32 v43, 0xbfb8aa3b, v131
	v_exp_f32_e32 v43, v43
	v_rcp_f32_e32 v129, v19
	v_add_f32_e32 v19, 1.0, v25
	v_rcp_f32_e32 v132, v19
	v_add_f32_e32 v19, 1.0, v43
	v_rcp_f32_e32 v133, v19
	v_pk_mul_f32 v[122:123], v[122:123], v[128:129]
	v_pk_mul_f32 v[134:135], v[124:125], v[124:125]
	v_pk_mul_f32 v[128:129], v[122:123], v[122:123]
	v_pk_mul_f32 v[130:131], v[130:131], v[132:133]
	v_pk_mul_f32 v[118:119], v[120:121], v[120:121]
	v_pk_mul_f32 v[132:133], v[130:131], v[130:131]
	s_waitcnt vmcnt(7)
	v_lshlrev_b32_e32 v140, 16, v237
	v_add_f32_e32 v19, v132, v133
	v_add_f32_e32 v19, v128, v19
	v_add_f32_e32 v19, v129, v19
	v_add_f32_e32 v19, v134, v19
	v_add_f32_e32 v19, v135, v19
	v_add_f32_e32 v19, v118, v19
	v_add_f32_e32 v19, v119, v19
	ds_bpermute_b32 v25, v23, v19
	v_and_b32_e32 v141, 0xffff0000, v237
	s_waitcnt lgkmcnt(0)
	v_add_f32_e32 v19, v19, v25
	ds_bpermute_b32 v25, v109, v19
	s_waitcnt lgkmcnt(0)
	v_add_f32_e32 v19, v19, v25
	ds_bpermute_b32 v25, v110, v19
	s_waitcnt lgkmcnt(0)
	v_add_f32_e32 v19, v19, v25
	ds_bpermute_b32 v25, v111, v19
	s_waitcnt lgkmcnt(0)
	v_add_f32_e32 v19, v19, v25
	v_add_f32_e32 v19, 0x358637bd, v19
	v_mul_f32_e32 v25, 0x4b800000, v19
	v_cmp_gt_f32_e64 s[8:9], s70, v19
	s_nop 1
	v_cndmask_b32_e64 v19, v19, v25, s[8:9]
	v_rsq_f32_e32 v19, v19
	s_nop 0
	v_mul_f32_e32 v25, 0x45800000, v19
	v_cndmask_b32_e64 v19, v19, v25, s[8:9]
	v_mul_f32_e32 v118, 0x3db504f3, v19
	v_pk_mul_f32 v[128:129], v[130:131], v[118:119] op_sel_hi:[1,0]
	v_pk_mul_f32 v[122:123], v[122:123], v[118:119] op_sel_hi:[1,0]
	v_pk_mul_f32 v[124:125], v[124:125], v[118:119] op_sel_hi:[1,0]
	v_pk_mul_f32 v[130:131], v[120:121], v[118:119] op_sel_hi:[1,0]
	v_cvt_pk_bf16_f32 v118, v128, v129
	v_cvt_pk_bf16_f32 v119, v122, v123
	v_cvt_pk_bf16_f32 v120, v124, v125
	v_cvt_pk_bf16_f32 v121, v130, v131
	v_add3_u32 v19, v196, v204, v26
	ds_write_b128 v19, v[118:121] offset:4096
	ds_read_b128 v[118:121], v108 offset:16
	ds_read_b128 v[122:125], v108 offset:1040
	ds_read_b128 v[128:131], v108 offset:2064
	ds_read_b128 v[132:135], v108 offset:3088
	ds_read_b128 v[144:147], v108
	s_waitcnt lgkmcnt(4)
	v_pk_fma_f32 v[120:121], v[120:121], v[140:141], 0 op_sel_hi:[1,1,0]
	s_waitcnt vmcnt(6)
	v_lshlrev_b32_e32 v140, 16, v229
	v_and_b32_e32 v141, 0xffff0000, v229
	s_waitcnt lgkmcnt(3)
	v_pk_fma_f32 v[120:121], v[124:125], v[140:141], v[120:121]
	s_waitcnt vmcnt(5)
	v_lshlrev_b32_e32 v124, 16, v233
	v_and_b32_e32 v125, 0xffff0000, v233
	s_waitcnt lgkmcnt(2)
	v_pk_fma_f32 v[120:121], v[130:131], v[124:125], v[120:121]
	s_waitcnt vmcnt(4)
	v_lshlrev_b32_e32 v124, 16, v241
	v_and_b32_e32 v125, 0xffff0000, v241
	s_waitcnt lgkmcnt(1)
	v_pk_fma_f32 v[120:121], v[134:135], v[124:125], v[120:121]
	ds_read_b128 v[148:151], v108 offset:1024
	ds_read_b128 v[152:155], v108 offset:2048
	ds_read_b128 v[156:159], v108 offset:3072
	v_mul_f32_e32 v3, 0xbfb8aa3b, v120
	v_exp_f32_e32 v3, v3
	v_mul_f32_e32 v7, 0xbfb8aa3b, v121
	v_exp_f32_e32 v7, v7
	v_and_b32_e32 v15, 0xffff0000, v227
	v_add_f32_e32 v3, 1.0, v3
	v_rcp_f32_e32 v124, v3
	v_add_f32_e32 v3, 1.0, v7
	v_rcp_f32_e32 v125, v3
	v_and_b32_e32 v7, 0xffff0000, v240
	v_pk_mul_f32 v[120:121], v[120:121], v[124:125]
	v_lshlrev_b32_e32 v124, 16, v236
	v_and_b32_e32 v125, 0xffff0000, v236
	v_pk_fma_f32 v[10:11], v[118:119], v[124:125], 0 op_sel_hi:[1,1,0]
	v_lshlrev_b32_e32 v118, 16, v228
	v_and_b32_e32 v119, 0xffff0000, v228
	v_pk_fma_f32 v[2:3], v[122:123], v[118:119], v[10:11]
	v_lshlrev_b32_e32 v10, 16, v232
	v_and_b32_e32 v11, 0xffff0000, v232
	v_pk_fma_f32 v[2:3], v[128:129], v[10:11], v[2:3]
	v_lshlrev_b32_e32 v6, 16, v240
	v_pk_fma_f32 v[2:3], v[132:133], v[6:7], v[2:3]
	v_lshlrev_b32_e32 v10, 16, v235
	v_mul_f32_e32 v6, 0xbfb8aa3b, v2
	v_mul_f32_e32 v7, 0xbfb8aa3b, v3
	v_exp_f32_e32 v6, v6
	v_exp_f32_e32 v7, v7
	v_and_b32_e32 v11, 0xffff0000, v235
	s_waitcnt lgkmcnt(3)
	v_pk_fma_f32 v[10:11], v[146:147], v[10:11], 0 op_sel_hi:[1,1,0]
	v_lshlrev_b32_e32 v14, 16, v227
	s_waitcnt lgkmcnt(2)
	v_pk_fma_f32 v[10:11], v[150:151], v[14:15], v[10:11]
	v_lshlrev_b32_e32 v14, 16, v231
	v_and_b32_e32 v15, 0xffff0000, v231
	s_waitcnt lgkmcnt(1)
	v_pk_fma_f32 v[10:11], v[154:155], v[14:15], v[10:11]
	v_lshlrev_b32_e32 v14, 16, v239
	v_and_b32_e32 v15, 0xffff0000, v239
	v_add_f32_e32 v6, 1.0, v6
	v_add_f32_e32 v7, 1.0, v7
	s_waitcnt lgkmcnt(0)
	v_pk_fma_f32 v[122:123], v[158:159], v[14:15], v[10:11]
	v_rcp_f32_e32 v6, v6
	v_rcp_f32_e32 v7, v7
	v_mul_f32_e32 v1, 0xbfb8aa3b, v122
	v_exp_f32_e32 v1, v1
	v_mul_f32_e32 v5, 0xbfb8aa3b, v123
	v_pk_mul_f32 v[124:125], v[2:3], v[6:7]
	v_lshlrev_b32_e32 v2, 16, v234
	v_and_b32_e32 v3, 0xffff0000, v234
	v_add_f32_e32 v1, 1.0, v1
	v_pk_fma_f32 v[2:3], v[144:145], v[2:3], 0 op_sel_hi:[1,1,0]
	v_lshlrev_b32_e32 v6, 16, v226
	v_and_b32_e32 v7, 0xffff0000, v226
	v_rcp_f32_e32 v128, v1
	v_pk_fma_f32 v[0:1], v[148:149], v[6:7], v[2:3]
	v_lshlrev_b32_e32 v2, 16, v230
	v_and_b32_e32 v3, 0xffff0000, v230
	v_exp_f32_e32 v5, v5
	v_pk_fma_f32 v[0:1], v[152:153], v[2:3], v[0:1]
	v_lshlrev_b32_e32 v2, 16, v238
	v_and_b32_e32 v3, 0xffff0000, v238
	v_pk_fma_f32 v[130:131], v[156:157], v[2:3], v[0:1]
	v_add_f32_e32 v19, 1.0, v5
	s_nop 0
	v_mul_f32_e32 v25, 0xbfb8aa3b, v130
	v_exp_f32_e32 v25, v25
	v_mul_f32_e32 v43, 0xbfb8aa3b, v131
	v_exp_f32_e32 v43, v43
	v_rcp_f32_e32 v129, v19
	v_add_f32_e32 v19, 1.0, v25
	v_rcp_f32_e32 v48, v19
	v_add_f32_e32 v19, 1.0, v43
	v_rcp_f32_e32 v49, v19
	v_pk_mul_f32 v[122:123], v[122:123], v[128:129]
	v_pk_mul_f32 v[132:133], v[124:125], v[124:125]
	v_pk_mul_f32 v[128:129], v[122:123], v[122:123]
	v_pk_mul_f32 v[48:49], v[130:131], v[48:49]
	v_pk_mul_f32 v[118:119], v[120:121], v[120:121]
	v_pk_mul_f32 v[130:131], v[48:49], v[48:49]
	s_nop 0
	v_add_f32_e32 v19, v130, v131
	v_add_f32_e32 v19, v128, v19
	v_add_f32_e32 v19, v129, v19
	v_add_f32_e32 v19, v132, v19
	v_add_f32_e32 v19, v133, v19
	v_add_f32_e32 v19, v118, v19
	v_add_f32_e32 v19, v119, v19
	ds_bpermute_b32 v25, v23, v19
	s_waitcnt lgkmcnt(0)
	v_add_f32_e32 v19, v19, v25
	ds_bpermute_b32 v25, v109, v19
	s_waitcnt lgkmcnt(0)
	v_add_f32_e32 v19, v19, v25
	ds_bpermute_b32 v25, v110, v19
	s_waitcnt lgkmcnt(0)
	v_add_f32_e32 v19, v19, v25
	ds_bpermute_b32 v25, v111, v19
	s_waitcnt lgkmcnt(0)
	v_add_f32_e32 v19, v19, v25
	v_add_f32_e32 v19, 0x358637bd, v19
	v_mul_f32_e32 v25, 0x4b800000, v19
	v_cmp_gt_f32_e64 s[8:9], s70, v19
	s_nop 1
	v_cndmask_b32_e64 v19, v19, v25, s[8:9]
	v_rsq_f32_e32 v19, v19
	s_nop 0
	v_mul_f32_e32 v25, 0x45800000, v19
	v_cndmask_b32_e64 v19, v19, v25, s[8:9]
	v_mul_f32_e32 v118, 0x3db504f3, v19
	v_pk_mul_f32 v[48:49], v[48:49], v[118:119] op_sel_hi:[1,0]
	v_pk_mul_f32 v[122:123], v[122:123], v[118:119] op_sel_hi:[1,0]
	v_pk_mul_f32 v[124:125], v[124:125], v[118:119] op_sel_hi:[1,0]
	v_pk_mul_f32 v[128:129], v[120:121], v[118:119] op_sel_hi:[1,0]
	v_cvt_pk_bf16_f32 v118, v48, v49
	v_cvt_pk_bf16_f32 v119, v122, v123
	v_cvt_pk_bf16_f32 v120, v124, v125
	v_cvt_pk_bf16_f32 v121, v128, v129
	v_add3_u32 v19, v196, v205, v26
	ds_write_b128 v19, v[118:121] offset:4096
	ds_read_b128 v[118:121], v108 offset:16
	ds_read_b128 v[122:125], v108 offset:1040
	ds_read_b128 v[128:131], v108 offset:2064
	ds_read_b128 v[132:135], v108 offset:3088
	ds_read_b128 v[144:147], v108
	s_waitcnt vmcnt(3)
	v_lshlrev_b32_e32 v48, 16, v219
	v_and_b32_e32 v49, 0xffff0000, v219
	s_waitcnt lgkmcnt(4)
	v_pk_fma_f32 v[48:49], v[120:121], v[48:49], 0 op_sel_hi:[1,1,0]
	s_waitcnt vmcnt(2)
	v_lshlrev_b32_e32 v120, 16, v211
	v_and_b32_e32 v121, 0xffff0000, v211
	s_waitcnt lgkmcnt(3)
	v_pk_fma_f32 v[48:49], v[124:125], v[120:121], v[48:49]
	s_waitcnt vmcnt(1)
	v_lshlrev_b32_e32 v120, 16, v215
	v_and_b32_e32 v121, 0xffff0000, v215
	s_waitcnt lgkmcnt(2)
	v_pk_fma_f32 v[48:49], v[130:131], v[120:121], v[48:49]
	s_waitcnt vmcnt(0)
	v_lshlrev_b32_e32 v120, 16, v223
	v_and_b32_e32 v121, 0xffff0000, v223
	s_waitcnt lgkmcnt(1)
	v_pk_fma_f32 v[48:49], v[134:135], v[120:121], v[48:49]
	ds_read_b128 v[148:151], v108 offset:1024
	ds_read_b128 v[152:155], v108 offset:2048
	ds_read_b128 v[156:159], v108 offset:3072
	v_mul_f32_e32 v3, 0xbfb8aa3b, v48
	v_exp_f32_e32 v3, v3
	v_mul_f32_e32 v7, 0xbfb8aa3b, v49
	v_exp_f32_e32 v7, v7
	v_and_b32_e32 v15, 0xffff0000, v217
	v_add_f32_e32 v3, 1.0, v3
	v_rcp_f32_e32 v120, v3
	v_add_f32_e32 v3, 1.0, v7
	v_rcp_f32_e32 v121, v3
	v_and_b32_e32 v7, 0xffff0000, v222
	v_mov_b32_e32 v25, v21
	v_pk_mul_f32 v[48:49], v[48:49], v[120:121]
	v_lshlrev_b32_e32 v120, 16, v218
	v_and_b32_e32 v121, 0xffff0000, v218
	v_pk_fma_f32 v[10:11], v[118:119], v[120:121], 0 op_sel_hi:[1,1,0]
	v_lshlrev_b32_e32 v118, 16, v210
	v_and_b32_e32 v119, 0xffff0000, v210
	v_pk_fma_f32 v[2:3], v[122:123], v[118:119], v[10:11]
	v_lshlrev_b32_e32 v10, 16, v214
	v_and_b32_e32 v11, 0xffff0000, v214
	v_pk_fma_f32 v[2:3], v[128:129], v[10:11], v[2:3]
	v_lshlrev_b32_e32 v6, 16, v222
	v_pk_fma_f32 v[2:3], v[132:133], v[6:7], v[2:3]
	v_lshlrev_b32_e32 v14, 16, v217
	v_mul_f32_e32 v6, 0xbfb8aa3b, v2
	v_exp_f32_e32 v10, v6
	v_mul_f32_e32 v6, 0xbfb8aa3b, v3
	s_waitcnt lgkmcnt(3)
	v_pk_fma_f32 v[14:15], v[146:147], v[14:15], 0 op_sel_hi:[1,1,0]
	v_lshlrev_b32_e32 v118, 16, v209
	v_and_b32_e32 v119, 0xffff0000, v209
	v_exp_f32_e32 v11, v6
	s_waitcnt lgkmcnt(2)
	v_pk_fma_f32 v[14:15], v[150:151], v[118:119], v[14:15]
	v_lshlrev_b32_e32 v118, 16, v213
	v_and_b32_e32 v119, 0xffff0000, v213
	s_waitcnt lgkmcnt(1)
	v_pk_fma_f32 v[14:15], v[154:155], v[118:119], v[14:15]
	v_lshlrev_b32_e32 v118, 16, v221
	v_and_b32_e32 v119, 0xffff0000, v221
	s_waitcnt lgkmcnt(0)
	v_pk_fma_f32 v[14:15], v[158:159], v[118:119], v[14:15]
	v_add_f32_e32 v10, 1.0, v10
	v_mul_f32_e32 v1, 0xbfb8aa3b, v14
	v_add_f32_e32 v11, 1.0, v11
	v_exp_f32_e32 v1, v1
	v_rcp_f32_e32 v10, v10
	v_rcp_f32_e32 v11, v11
	v_mul_f32_e32 v5, 0xbfb8aa3b, v15
	v_exp_f32_e32 v5, v5
	v_lshlrev_b32_e32 v118, 16, v216
	v_and_b32_e32 v119, 0xffff0000, v216
	v_add_f32_e32 v1, 1.0, v1
	v_pk_fma_f32 v[8:9], v[144:145], v[118:119], 0 op_sel_hi:[1,1,0]
	v_lshlrev_b32_e32 v118, 16, v208
	v_and_b32_e32 v119, 0xffff0000, v208
	v_pk_mul_f32 v[2:3], v[2:3], v[10:11]
	v_rcp_f32_e32 v10, v1
	v_pk_fma_f32 v[0:1], v[148:149], v[118:119], v[8:9]
	v_lshlrev_b32_e32 v8, 16, v212
	v_and_b32_e32 v9, 0xffff0000, v212
	v_add_f32_e32 v11, 1.0, v5
	v_pk_fma_f32 v[0:1], v[152:153], v[8:9], v[0:1]
	v_lshlrev_b32_e32 v4, 16, v220
	v_and_b32_e32 v5, 0xffff0000, v220
	v_pk_fma_f32 v[0:1], v[156:157], v[4:5], v[0:1]
	v_rcp_f32_e32 v11, v11
	v_mul_f32_e32 v4, 0xbfb8aa3b, v0
	v_mul_f32_e32 v5, 0xbfb8aa3b, v1
	v_exp_f32_e32 v4, v4
	v_exp_f32_e32 v5, v5
	v_pk_mul_f32 v[10:11], v[14:15], v[10:11]
	v_pk_mul_f32 v[8:9], v[2:3], v[2:3]
	v_add_f32_e32 v4, 1.0, v4
	v_add_f32_e32 v5, 1.0, v5
	v_rcp_f32_e32 v4, v4
	v_rcp_f32_e32 v5, v5
	v_pk_mul_f32 v[12:13], v[10:11], v[10:11]
	v_pk_mul_f32 v[6:7], v[48:49], v[48:49]
	v_pk_mul_f32 v[0:1], v[0:1], v[4:5]
	s_nop 0
	v_pk_mul_f32 v[4:5], v[0:1], v[0:1]
	s_nop 0
	v_add_f32_e32 v4, v4, v5
	v_add_f32_e32 v4, v12, v4
	v_add_f32_e32 v4, v13, v4
	v_add_f32_e32 v4, v8, v4
	v_add_f32_e32 v4, v9, v4
	v_add_f32_e32 v4, v6, v4
	v_add_f32_e32 v4, v7, v4
	ds_bpermute_b32 v5, v23, v4
	s_waitcnt lgkmcnt(0)
	v_add_f32_e32 v4, v4, v5
	ds_bpermute_b32 v5, v109, v4
	s_waitcnt lgkmcnt(0)
	v_add_f32_e32 v4, v4, v5
	ds_bpermute_b32 v5, v110, v4
	s_waitcnt lgkmcnt(0)
	v_add_f32_e32 v4, v4, v5
	ds_bpermute_b32 v5, v111, v4
	s_waitcnt lgkmcnt(0)
	v_add_f32_e32 v4, v4, v5
	v_add_f32_e32 v4, 0x358637bd, v4
	v_mul_f32_e32 v5, 0x4b800000, v4
	v_cmp_gt_f32_e64 s[8:9], s70, v4
	s_nop 1
	v_cndmask_b32_e64 v4, v4, v5, s[8:9]
	v_rsq_f32_e32 v4, v4
	s_nop 0
	v_mul_f32_e32 v5, 0x45800000, v4
	v_cndmask_b32_e64 v4, v4, v5, s[8:9]
	v_mul_f32_e32 v4, 0x3db504f3, v4
	v_pk_mul_f32 v[0:1], v[0:1], v[4:5] op_sel_hi:[1,0]
	v_pk_mul_f32 v[6:7], v[10:11], v[4:5] op_sel_hi:[1,0]
	v_pk_mul_f32 v[2:3], v[2:3], v[4:5] op_sel_hi:[1,0]
	v_pk_mul_f32 v[4:5], v[48:49], v[4:5] op_sel_hi:[1,0]
	v_cvt_pk_bf16_f32 v0, v0, v1
	v_cvt_pk_bf16_f32 v1, v6, v7
	v_cvt_pk_bf16_f32 v2, v2, v3
	v_cvt_pk_bf16_f32 v3, v4, v5
	v_add3_u32 v4, v196, v206, v26
	ds_write_b128 v4, v[0:3] offset:4096
	v_mov_b64_e32 v[2:3], 0x20600000
	v_mov_b64_e32 v[0:1], 0x5000
	v_mov_b64_e32 v[4:5], v[24:25]
	s_and_saveexec_b64 s[8:9], vcc
	v_mov_b32_e32 v19, v21
	v_mov_b64_e32 v[2:3], 0x8100000
	v_mov_b64_e32 v[0:1], 0x6000
	v_mov_b64_e32 v[4:5], v[18:19]
	v_mov_b64_e32 v[16:17], v[36:37]
	s_or_b64 exec, exec, s[8:9]
	v_mad_u64_u32 v[6:7], s[8:9], v46, v114, 0
	v_add_u32_e32 v7, v7, v20
	v_lshl_or_b32 v20, v113, 1, v192
	v_lshl_add_u64 v[2:3], s[82:83], 0, v[2:3]
	v_lshl_add_u64 v[2:3], v[2:3], 0, v[20:21]
	v_lshl_add_u64 v[4:5], v[16:17], 0, v[4:5]
	v_mad_u64_u32 v[2:3], s[8:9], v4, v0, v[2:3]
	v_lshl_add_u64 v[10:11], s[14:15], 0, v[20:21]
	v_lshl_add_u64 v[12:13], s[68:69], 0, v[20:21]
	v_mov_b32_e32 v4, v3
	v_mad_u64_u32 v[0:1], s[8:9], v5, v0, v[4:5]
	v_cndmask_b32_e64 v5, v11, v13, s[4:5]
	v_cndmask_b32_e64 v4, v10, v12, s[4:5]
	v_mov_b32_e32 v3, v0
	v_lshl_add_u64 v[4:5], v[4:5], 0, v[6:7]
	global_load_dwordx4 v[0:3], v[2:3], off
	s_nop 0
	global_load_dwordx4 v[4:7], v[4:5], off
	s_and_saveexec_b64 s[4:5], s[6:7]
	s_xor_b64 s[4:5], exec, s[4:5]
	v_mov_b32_e32 v43, v21
	v_lshl_add_u64 v[10:11], v[36:37], 0, v[42:43]
	v_mad_u64_u32 v[8:9], s[6:7], v10, s29, v[12:13]
	v_mov_b32_e32 v10, v9
	v_mad_u64_u32 v[10:11], s[6:7], v11, s29, v[10:11]
	v_mov_b32_e32 v9, v10
	s_andn2_saveexec_b64 s[4:5], s[4:5]
	v_lshl_add_u64 v[8:9], v[10:11], 0, v[44:45]
	s_mov_b64 s[6:7], 0xa000
	v_lshl_add_u64 v[8:9], v[8:9], 0, s[6:7]
	s_or_b64 exec, exec, s[4:5]
	global_load_dwordx4 v[8:11], v[8:9], off
	v_mad_u64_u32 v[14:15], s[4:5], v115, s29, 0
	v_add_u32_e32 v15, v15, v112
	v_lshl_add_u64 v[14:15], v[12:13], 0, v[14:15]
	global_load_dwordx4 v[14:17], v[14:15], off
	v_or_b32_e32 v244, 16, v24
	v_or_b32_e32 v240, v36, v244
	v_mad_u64_u32 v[240:241], s[98:99], v240, s29, v[12:13]
	v_add_u32_e32 v241, v112, v241
	global_load_dwordx4 v[240:243], v[240:241], off
	v_add_u32_e32 v226, 13, v24
	v_or_b32_e32 v226, v36, v226
	v_add_u32_e32 v230, 14, v24
	v_mad_u64_u32 v[226:227], s[98:99], v226, s29, v[12:13]
	v_or_b32_e32 v230, v36, v230
	v_add_u32_e32 v234, 15, v24
	v_add_u32_e32 v227, v112, v227
	v_mad_u64_u32 v[230:231], s[98:99], v230, s29, v[12:13]
	v_or_b32_e32 v234, v36, v234
	global_load_dwordx4 v[226:229], v[226:227], off
	v_add_u32_e32 v231, v112, v231
	v_mad_u64_u32 v[234:235], s[98:99], v234, s29, v[12:13]
	global_load_dwordx4 v[230:233], v[230:231], off
	v_add_u32_e32 v235, v112, v235
	global_load_dwordx4 v[234:237], v[234:235], off
	s_waitcnt vmcnt(6)
	v_cndmask_b32_e64 v113, v4, 0, s[24:25]
	v_cndmask_b32_e64 v114, v5, 0, s[24:25]
	v_cndmask_b32_e64 v115, v6, 0, s[24:25]
	v_cndmask_b32_e64 v126, v7, 0, s[24:25]
	v_cndmask_b32_e64 v140, v0, 0, s[10:11]
	v_cndmask_b32_e64 v141, v1, 0, s[10:11]
	v_cndmask_b32_e64 v144, v2, 0, s[10:11]
	v_cndmask_b32_e64 v19, v3, 0, s[10:11]
	v_lshlrev_b32_e32 v18, 16, v19
	v_and_b32_e32 v19, 0xffff0000, v19
	v_bfe_u32 v20, v38, 6, 2
	s_waitcnt vmcnt(5)
	v_cndmask_b32_e64 v25, v8, 0, s[0:1]
	v_cndmask_b32_e64 v46, v9, 0, s[0:1]
	v_cndmask_b32_e64 v48, v10, 0, s[0:1]
	v_cndmask_b32_e64 v49, v11, 0, s[0:1]
	ds_read_b128 v[0:3], v108 offset:512
	ds_read_b128 v[4:7], v108 offset:528
	ds_read_b128 v[8:11], v108 offset:1536
	ds_read_b128 v[42:45], v108 offset:1552
	ds_read_b128 v[118:121], v108 offset:2560
	ds_read_b128 v[122:125], v108 offset:2576
	ds_read_b128 v[128:131], v108 offset:3584
	ds_read_b128 v[132:135], v108 offset:3600
	s_waitcnt lgkmcnt(6)
	v_pk_fma_f32 v[6:7], v[6:7], v[18:19], 0 op_sel_hi:[1,1,0]
	v_lshlrev_b32_e32 v18, 16, v126
	v_and_b32_e32 v19, 0xffff0000, v126
	s_waitcnt lgkmcnt(4)
	v_pk_fma_f32 v[6:7], v[44:45], v[18:19], v[6:7]
	v_lshlrev_b32_e32 v18, 16, v49
	v_and_b32_e32 v19, 0xffff0000, v49
	s_waitcnt lgkmcnt(2)
	v_pk_fma_f32 v[6:7], v[124:125], v[18:19], v[6:7]
	s_waitcnt vmcnt(4)
	v_lshlrev_b32_e32 v18, 16, v17
	v_and_b32_e32 v19, 0xffff0000, v17
	v_lshlrev_b32_e32 v44, 16, v144
	v_and_b32_e32 v45, 0xffff0000, v144
	s_waitcnt lgkmcnt(0)
	v_pk_fma_f32 v[6:7], v[134:135], v[18:19], v[6:7]
	v_pk_fma_f32 v[4:5], v[4:5], v[44:45], 0 op_sel_hi:[1,1,0]
	v_lshlrev_b32_e32 v44, 16, v115
	v_and_b32_e32 v45, 0xffff0000, v115
	v_mul_f32_e32 v17, 0xbfb8aa3b, v6
	v_pk_fma_f32 v[4:5], v[42:43], v[44:45], v[4:5]
	v_lshlrev_b32_e32 v42, 16, v48
	v_and_b32_e32 v43, 0xffff0000, v48
	v_exp_f32_e32 v17, v17
	v_pk_fma_f32 v[4:5], v[122:123], v[42:43], v[4:5]
	v_lshlrev_b32_e32 v42, 16, v16
	v_and_b32_e32 v43, 0xffff0000, v16
	v_pk_fma_f32 v[4:5], v[132:133], v[42:43], v[4:5]
	v_lshlrev_b32_e32 v42, 16, v141
	v_and_b32_e32 v43, 0xffff0000, v141
	v_pk_fma_f32 v[2:3], v[2:3], v[42:43], 0 op_sel_hi:[1,1,0]
	v_lshlrev_b32_e32 v42, 16, v114
	v_and_b32_e32 v43, 0xffff0000, v114
	v_pk_fma_f32 v[2:3], v[10:11], v[42:43], v[2:3]
	v_lshlrev_b32_e32 v42, 16, v140
	v_and_b32_e32 v43, 0xffff0000, v140
	v_add_f32_e32 v17, 1.0, v17
	v_pk_fma_f32 v[0:1], v[0:1], v[42:43], 0 op_sel_hi:[1,1,0]
	v_lshlrev_b32_e32 v42, 16, v113
	v_and_b32_e32 v43, 0xffff0000, v113
	v_rcp_f32_e32 v18, v17
	v_mul_f32_e32 v17, 0xbfb8aa3b, v7
	v_pk_fma_f32 v[0:1], v[8:9], v[42:43], v[0:1]
	v_lshlrev_b32_e32 v8, 16, v25
	v_and_b32_e32 v9, 0xffff0000, v25
	v_exp_f32_e32 v17, v17
	v_lshlrev_b32_e32 v10, 16, v46
	v_and_b32_e32 v11, 0xffff0000, v46
	v_pk_fma_f32 v[0:1], v[118:119], v[8:9], v[0:1]
	v_lshlrev_b32_e32 v8, 16, v14
	v_and_b32_e32 v9, 0xffff0000, v14
	v_pk_fma_f32 v[2:3], v[120:121], v[10:11], v[2:3]
	v_lshlrev_b32_e32 v10, 16, v15
	v_and_b32_e32 v11, 0xffff0000, v15
	v_pk_fma_f32 v[0:1], v[128:129], v[8:9], v[0:1]
	v_pk_fma_f32 v[2:3], v[130:131], v[10:11], v[2:3]
	v_mul_f32_e32 v8, 0xbfb8aa3b, v0
	v_mul_f32_e32 v9, 0xbfb8aa3b, v1
	v_mul_f32_e32 v10, 0xbfb8aa3b, v2
	v_mul_f32_e32 v11, 0xbfb8aa3b, v3
	v_exp_f32_e32 v8, v8
	v_exp_f32_e32 v9, v9
	v_add_f32_e32 v17, 1.0, v17
	v_exp_f32_e32 v10, v10
	v_exp_f32_e32 v11, v11
	v_rcp_f32_e32 v19, v17
	v_mul_f32_e32 v16, 0xbfb8aa3b, v4
	v_mul_f32_e32 v17, 0xbfb8aa3b, v5
	v_exp_f32_e32 v16, v16
	v_exp_f32_e32 v17, v17
	v_add_f32_e32 v8, 1.0, v8
	v_add_f32_e32 v9, 1.0, v9
	v_add_f32_e32 v10, 1.0, v10
	v_add_f32_e32 v11, 1.0, v11
	v_rcp_f32_e32 v8, v8
	v_rcp_f32_e32 v9, v9
	v_rcp_f32_e32 v10, v10
	v_rcp_f32_e32 v11, v11
	v_add_f32_e32 v16, 1.0, v16
	v_add_f32_e32 v17, 1.0, v17
	v_rcp_f32_e32 v16, v16
	v_rcp_f32_e32 v17, v17
	v_pk_mul_f32 v[0:1], v[0:1], v[8:9]
	v_pk_mul_f32 v[2:3], v[2:3], v[10:11]
	v_pk_mul_f32 v[8:9], v[0:1], v[0:1]
	v_pk_mul_f32 v[10:11], v[2:3], v[2:3]
	v_add_f32_e32 v8, v8, v9
	v_pk_mul_f32 v[4:5], v[4:5], v[16:17]
	v_add_f32_e32 v8, v10, v8
	v_pk_mul_f32 v[16:17], v[4:5], v[4:5]
	v_add_f32_e32 v8, v11, v8
	v_pk_mul_f32 v[6:7], v[6:7], v[18:19]
	v_add_f32_e32 v8, v16, v8
	v_pk_mul_f32 v[18:19], v[6:7], v[6:7]
	v_add_f32_e32 v8, v17, v8
	v_add_f32_e32 v8, v18, v8
	v_add_f32_e32 v8, v19, v8
	ds_bpermute_b32 v9, v23, v8
	v_or_b32_e32 v25, 16, v24
	s_waitcnt lgkmcnt(0)
	v_add_f32_e32 v8, v8, v9
	ds_bpermute_b32 v9, v109, v8
	s_waitcnt lgkmcnt(0)
	v_add_f32_e32 v8, v8, v9
	ds_bpermute_b32 v9, v110, v8
	s_waitcnt lgkmcnt(0)
	v_add_f32_e32 v8, v8, v9
	ds_bpermute_b32 v9, v111, v8
	s_waitcnt lgkmcnt(0)
	v_add_f32_e32 v8, v8, v9
	v_add_f32_e32 v8, 0x358637bd, v8
	v_cmp_gt_f32_e32 vcc, s70, v8
	v_mul_f32_e32 v9, 0x4b800000, v8
	s_nop 0
	v_cndmask_b32_e32 v8, v8, v9, vcc
	v_rsq_f32_e32 v8, v8
	s_nop 0
	v_mul_f32_e32 v9, 0x45800000, v8
	v_cndmask_b32_e32 v8, v8, v9, vcc
	v_pk_mul_f32 v[0:1], v[0:1], v[8:9] op_sel_hi:[1,0]
	v_pk_mul_f32 v[2:3], v[2:3], v[8:9] op_sel_hi:[1,0]
	v_pk_mul_f32 v[4:5], v[4:5], v[8:9] op_sel_hi:[1,0]
	v_pk_mul_f32 v[6:7], v[6:7], v[8:9] op_sel_hi:[1,0]
	v_cvt_pk_bf16_f32 v0, v0, v1
	v_cvt_pk_bf16_f32 v1, v2, v3
	v_cvt_pk_bf16_f32 v2, v4, v5
	v_cvt_pk_bf16_f32 v3, v6, v7
	ds_write_b128 v117, v[0:3] offset:21504
	v_add_u32_e32 v216, 31, v24
	v_or_b32_e32 v216, v36, v216
	v_mad_u64_u32 v[216:217], s[98:99], v216, s29, v[12:13]
	v_or3_b32 v222, v24, v36, 32
	v_add_u32_e32 v217, v112, v217
	v_mad_u64_u32 v[222:223], s[98:99], v222, s29, v[12:13]
	v_add_u32_e32 v223, v112, v223
	global_load_dwordx4 v[222:225], v[222:223], off
	v_add_u32_e32 v208, 29, v24
	v_or_b32_e32 v208, v36, v208
	v_add_u32_e32 v212, 30, v24
	v_mad_u64_u32 v[208:209], s[98:99], v208, s29, v[12:13]
	v_or_b32_e32 v212, v36, v212
	v_add_u32_e32 v209, v112, v209
	v_mad_u64_u32 v[212:213], s[98:99], v212, s29, v[12:13]
	global_load_dwordx4 v[208:211], v[208:209], off
	v_add_u32_e32 v213, v112, v213
	global_load_dwordx4 v[212:215], v[212:213], off
	s_nop 0
	global_load_dwordx4 v[216:219], v[216:217], off
	ds_read_b128 v[42:45], v108 offset:512
	ds_read_b128 v[118:121], v108 offset:528
	ds_read_b128 v[122:125], v108 offset:1536
	ds_read_b128 v[128:131], v108 offset:1552
	ds_read_b128 v[132:135], v108 offset:2560
	ds_read_b128 v[144:147], v108 offset:2576
	ds_read_b128 v[148:151], v108 offset:3584
	ds_read_b128 v[152:155], v108 offset:3600
	s_waitcnt vmcnt(6)
	v_lshlrev_b32_e32 v18, 16, v229
	v_and_b32_e32 v19, 0xffff0000, v229
	s_waitcnt lgkmcnt(6)
	v_pk_fma_f32 v[18:19], v[120:121], v[18:19], 0 op_sel_hi:[1,1,0]
	v_lshlrev_b32_e32 v114, 16, v228
	s_waitcnt vmcnt(5)
	v_lshlrev_b32_e32 v48, 16, v233
	v_and_b32_e32 v49, 0xffff0000, v233
	s_waitcnt lgkmcnt(4)
	v_pk_fma_f32 v[18:19], v[130:131], v[48:49], v[18:19]
	s_waitcnt vmcnt(4)
	v_lshlrev_b32_e32 v48, 16, v237
	v_and_b32_e32 v49, 0xffff0000, v237
	s_waitcnt lgkmcnt(2)
	v_pk_fma_f32 v[18:19], v[146:147], v[48:49], v[18:19]
	v_lshlrev_b32_e32 v48, 16, v243
	v_and_b32_e32 v49, 0xffff0000, v243
	s_waitcnt lgkmcnt(0)
	v_pk_fma_f32 v[18:19], v[154:155], v[48:49], v[18:19]
	v_and_b32_e32 v115, 0xffff0000, v228
	v_mul_f32_e32 v3, 0xbfb8aa3b, v18
	v_exp_f32_e32 v3, v3
	v_and_b32_e32 v7, 0xffff0000, v236
	v_and_b32_e32 v11, 0xffff0000, v227
	v_and_b32_e32 v17, 0xffff0000, v231
	v_add_f32_e32 v3, 1.0, v3
	v_rcp_f32_e32 v48, v3
	v_mul_f32_e32 v3, 0xbfb8aa3b, v19
	v_exp_f32_e32 v3, v3
	s_nop 0
	v_add_f32_e32 v3, 1.0, v3
	v_rcp_f32_e32 v49, v3
	v_pk_fma_f32 v[2:3], v[118:119], v[114:115], 0 op_sel_hi:[1,1,0]
	v_lshlrev_b32_e32 v114, 16, v232
	v_and_b32_e32 v115, 0xffff0000, v232
	v_pk_fma_f32 v[2:3], v[128:129], v[114:115], v[2:3]
	v_lshlrev_b32_e32 v6, 16, v236
	v_lshlrev_b32_e32 v10, 16, v227
	v_pk_fma_f32 v[2:3], v[144:145], v[6:7], v[2:3]
	v_lshlrev_b32_e32 v6, 16, v242
	v_and_b32_e32 v7, 0xffff0000, v242
	v_pk_fma_f32 v[10:11], v[44:45], v[10:11], 0 op_sel_hi:[1,1,0]
	v_lshlrev_b32_e32 v16, 16, v231
	v_pk_fma_f32 v[10:11], v[124:125], v[16:17], v[10:11]
	v_lshlrev_b32_e32 v16, 16, v235
	v_and_b32_e32 v17, 0xffff0000, v235
	v_pk_fma_f32 v[10:11], v[134:135], v[16:17], v[10:11]
	v_lshlrev_b32_e32 v16, 16, v241
	v_and_b32_e32 v17, 0xffff0000, v241
	v_pk_fma_f32 v[10:11], v[150:151], v[16:17], v[10:11]
	v_lshlrev_b32_e32 v44, 16, v226
	v_mul_f32_e32 v1, 0xbfb8aa3b, v10
	v_exp_f32_e32 v1, v1
	v_and_b32_e32 v45, 0xffff0000, v226
	v_and_b32_e32 v5, 0xffff0000, v234
	v_pk_fma_f32 v[2:3], v[152:153], v[6:7], v[2:3]
	v_add_f32_e32 v1, 1.0, v1
	v_rcp_f32_e32 v16, v1
	v_mul_f32_e32 v1, 0xbfb8aa3b, v11
	v_exp_f32_e32 v1, v1
	v_mul_f32_e32 v6, 0xbfb8aa3b, v2
	v_mul_f32_e32 v7, 0xbfb8aa3b, v3
	v_exp_f32_e32 v6, v6
	v_add_f32_e32 v1, 1.0, v1
	v_rcp_f32_e32 v17, v1
	v_pk_fma_f32 v[0:1], v[42:43], v[44:45], 0 op_sel_hi:[1,1,0]
	v_lshlrev_b32_e32 v42, 16, v230
	v_and_b32_e32 v43, 0xffff0000, v230
	v_pk_fma_f32 v[0:1], v[122:123], v[42:43], v[0:1]
	v_lshlrev_b32_e32 v4, 16, v234
	v_pk_fma_f32 v[0:1], v[132:133], v[4:5], v[0:1]
	v_lshlrev_b32_e32 v4, 16, v240
	v_and_b32_e32 v5, 0xffff0000, v240
	v_pk_fma_f32 v[0:1], v[148:149], v[4:5], v[0:1]
	v_exp_f32_e32 v7, v7
	v_mul_f32_e32 v4, 0xbfb8aa3b, v0
	v_mul_f32_e32 v5, 0xbfb8aa3b, v1
	v_exp_f32_e32 v4, v4
	v_exp_f32_e32 v5, v5
	v_add_f32_e32 v6, 1.0, v6
	v_add_f32_e32 v7, 1.0, v7
	v_add_f32_e32 v4, 1.0, v4
	v_add_f32_e32 v5, 1.0, v5
	v_rcp_f32_e32 v4, v4
	v_rcp_f32_e32 v5, v5
	v_rcp_f32_e32 v6, v6
	v_rcp_f32_e32 v7, v7
	v_pk_mul_f32 v[10:11], v[10:11], v[16:17]
	v_pk_mul_f32 v[0:1], v[0:1], v[4:5]
	v_pk_mul_f32 v[16:17], v[10:11], v[10:11]
	v_pk_mul_f32 v[4:5], v[0:1], v[0:1]
	v_pk_mul_f32 v[2:3], v[2:3], v[6:7]
	v_add_f32_e32 v4, v4, v5
	v_add_f32_e32 v4, v16, v4
	v_pk_mul_f32 v[6:7], v[2:3], v[2:3]
	v_add_f32_e32 v4, v17, v4
	v_pk_mul_f32 v[18:19], v[18:19], v[48:49]
	v_add_f32_e32 v4, v6, v4
	v_pk_mul_f32 v[48:49], v[18:19], v[18:19]
	v_add_f32_e32 v4, v7, v4
	v_add_f32_e32 v4, v48, v4
	v_add_f32_e32 v4, v49, v4
	ds_bpermute_b32 v5, v23, v4
	s_waitcnt lgkmcnt(0)
	v_add_f32_e32 v4, v4, v5
	ds_bpermute_b32 v5, v109, v4
	s_waitcnt lgkmcnt(0)
	v_add_f32_e32 v4, v4, v5
	ds_bpermute_b32 v5, v110, v4
	s_waitcnt lgkmcnt(0)
	v_add_f32_e32 v4, v4, v5
	ds_bpermute_b32 v5, v111, v4
	s_waitcnt lgkmcnt(0)
	v_add_f32_e32 v4, v4, v5
	v_add_f32_e32 v4, 0x358637bd, v4
	v_cmp_gt_f32_e32 vcc, s70, v4
	v_mul_f32_e32 v5, 0x4b800000, v4
	s_nop 0
	v_cndmask_b32_e32 v4, v4, v5, vcc
	v_rsq_f32_e32 v4, v4
	s_nop 0
	v_mul_f32_e32 v5, 0x45800000, v4
	v_cndmask_b32_e32 v4, v4, v5, vcc
	v_pk_mul_f32 v[0:1], v[0:1], v[4:5] op_sel_hi:[1,0]
	v_pk_mul_f32 v[6:7], v[10:11], v[4:5] op_sel_hi:[1,0]
	v_pk_mul_f32 v[2:3], v[2:3], v[4:5] op_sel_hi:[1,0]
	v_pk_mul_f32 v[4:5], v[18:19], v[4:5] op_sel_hi:[1,0]
	v_cvt_pk_bf16_f32 v2, v2, v3
	v_cvt_pk_bf16_f32 v3, v4, v5
	v_mul_u32_u24_e32 v4, 0x110, v25
	v_cvt_pk_bf16_f32 v0, v0, v1
	v_cvt_pk_bf16_f32 v1, v6, v7
	v_add3_u32 v25, v196, v4, v26
	ds_write_b128 v25, v[0:3] offset:21504
	s_waitcnt vmcnt(2)
	v_lshlrev_b32_e32 v18, 16, v211
	v_bfe_u32 v234, v38, 4, 4
	v_add_u32_e32 v226, 45, v234
	v_or_b32_e32 v226, v36, v226
	v_add_u32_e32 v230, 46, v234
	v_or_b32_e32 v244, 48, v234
	v_mad_u64_u32 v[226:227], s[98:99], v226, s29, v[12:13]
	v_or_b32_e32 v230, v36, v230
	v_add_u32_e32 v234, 47, v234
	v_add_u32_e32 v227, v112, v227
	v_mad_u64_u32 v[230:231], s[98:99], v230, s29, v[12:13]
	v_or_b32_e32 v234, v36, v234
	global_load_dwordx4 v[226:229], v[226:227], off
	v_add_u32_e32 v231, v112, v231
	v_mad_u64_u32 v[234:235], s[98:99], v234, s29, v[12:13]
	v_or_b32_e32 v240, v36, v244
	global_load_dwordx4 v[230:233], v[230:231], off
	v_add_u32_e32 v235, v112, v235
	v_mad_u64_u32 v[238:239], s[98:99], v240, s29, v[12:13]
	global_load_dwordx4 v[234:237], v[234:235], off
	v_add_u32_e32 v239, v112, v239
	global_load_dwordx4 v[238:241], v[238:239], off
	ds_read_b128 v[42:45], v108 offset:512
	ds_read_b128 v[118:121], v108 offset:528
	ds_read_b128 v[122:125], v108 offset:1536
	ds_read_b128 v[128:131], v108 offset:1552
	ds_read_b128 v[132:135], v108 offset:2560
	ds_read_b128 v[144:147], v108 offset:2576
	ds_read_b128 v[148:151], v108 offset:3584
	ds_read_b128 v[152:155], v108 offset:3600
	v_and_b32_e32 v19, 0xffff0000, v211
	s_waitcnt lgkmcnt(6)
	v_pk_fma_f32 v[18:19], v[120:121], v[18:19], 0 op_sel_hi:[1,1,0]
	s_waitcnt vmcnt(5)
	v_lshlrev_b32_e32 v48, 16, v215
	v_and_b32_e32 v49, 0xffff0000, v215
	s_waitcnt lgkmcnt(4)
	v_pk_fma_f32 v[18:19], v[130:131], v[48:49], v[18:19]
	v_lshlrev_b32_e32 v114, 16, v210
	v_and_b32_e32 v115, 0xffff0000, v210
	s_waitcnt vmcnt(4)
	v_lshlrev_b32_e32 v48, 16, v219
	v_and_b32_e32 v49, 0xffff0000, v219
	s_waitcnt lgkmcnt(2)
	v_pk_fma_f32 v[18:19], v[146:147], v[48:49], v[18:19]
	v_lshlrev_b32_e32 v48, 16, v225
	v_and_b32_e32 v49, 0xffff0000, v225
	s_waitcnt lgkmcnt(0)
	v_pk_fma_f32 v[18:19], v[154:155], v[48:49], v[18:19]
	v_and_b32_e32 v7, 0xffff0000, v218
	v_mul_f32_e32 v3, 0xbfb8aa3b, v18
	v_exp_f32_e32 v3, v3
	v_and_b32_e32 v11, 0xffff0000, v209
	v_and_b32_e32 v17, 0xffff0000, v213
	v_add_f32_e32 v3, 1.0, v3
	v_rcp_f32_e32 v48, v3
	v_mul_f32_e32 v3, 0xbfb8aa3b, v19
	v_exp_f32_e32 v3, v3
	s_nop 0
	v_add_f32_e32 v3, 1.0, v3
	v_rcp_f32_e32 v49, v3
	v_pk_fma_f32 v[2:3], v[118:119], v[114:115], 0 op_sel_hi:[1,1,0]
	v_lshlrev_b32_e32 v114, 16, v214
	v_and_b32_e32 v115, 0xffff0000, v214
	v_pk_fma_f32 v[2:3], v[128:129], v[114:115], v[2:3]
	v_lshlrev_b32_e32 v6, 16, v218
	v_lshlrev_b32_e32 v10, 16, v209
	v_pk_fma_f32 v[2:3], v[144:145], v[6:7], v[2:3]
	v_lshlrev_b32_e32 v6, 16, v224
	v_and_b32_e32 v7, 0xffff0000, v224
	v_pk_fma_f32 v[10:11], v[44:45], v[10:11], 0 op_sel_hi:[1,1,0]
	v_lshlrev_b32_e32 v16, 16, v213
	v_pk_fma_f32 v[10:11], v[124:125], v[16:17], v[10:11]
	v_lshlrev_b32_e32 v16, 16, v217
	v_and_b32_e32 v17, 0xffff0000, v217
	v_pk_fma_f32 v[10:11], v[134:135], v[16:17], v[10:11]
	v_lshlrev_b32_e32 v16, 16, v223
	v_and_b32_e32 v17, 0xffff0000, v223
	v_pk_fma_f32 v[10:11], v[150:151], v[16:17], v[10:11]
	v_lshlrev_b32_e32 v44, 16, v208
	v_mul_f32_e32 v1, 0xbfb8aa3b, v10
	v_exp_f32_e32 v1, v1
	v_and_b32_e32 v45, 0xffff0000, v208
	v_and_b32_e32 v5, 0xffff0000, v216
	v_pk_fma_f32 v[2:3], v[152:153], v[6:7], v[2:3]
	v_add_f32_e32 v1, 1.0, v1
	v_rcp_f32_e32 v16, v1
	v_mul_f32_e32 v1, 0xbfb8aa3b, v11
	v_exp_f32_e32 v1, v1
	v_mul_f32_e32 v6, 0xbfb8aa3b, v2
	v_mul_f32_e32 v7, 0xbfb8aa3b, v3
	v_exp_f32_e32 v6, v6
	v_add_f32_e32 v1, 1.0, v1
	v_rcp_f32_e32 v17, v1
	v_pk_fma_f32 v[0:1], v[42:43], v[44:45], 0 op_sel_hi:[1,1,0]
	v_lshlrev_b32_e32 v42, 16, v212
	v_and_b32_e32 v43, 0xffff0000, v212
	v_pk_fma_f32 v[0:1], v[122:123], v[42:43], v[0:1]
	v_lshlrev_b32_e32 v4, 16, v216
	v_pk_fma_f32 v[0:1], v[132:133], v[4:5], v[0:1]
	v_lshlrev_b32_e32 v4, 16, v222
	v_and_b32_e32 v5, 0xffff0000, v222
	v_pk_fma_f32 v[0:1], v[148:149], v[4:5], v[0:1]
	v_exp_f32_e32 v7, v7
	v_mul_f32_e32 v4, 0xbfb8aa3b, v0
	v_mul_f32_e32 v5, 0xbfb8aa3b, v1
	v_exp_f32_e32 v4, v4
	v_exp_f32_e32 v5, v5
	v_add_f32_e32 v6, 1.0, v6
	v_add_f32_e32 v7, 1.0, v7
	v_add_f32_e32 v4, 1.0, v4
	v_add_f32_e32 v5, 1.0, v5
	v_rcp_f32_e32 v4, v4
	v_rcp_f32_e32 v5, v5
	v_rcp_f32_e32 v6, v6
	v_rcp_f32_e32 v7, v7
	v_pk_mul_f32 v[10:11], v[10:11], v[16:17]
	v_pk_mul_f32 v[0:1], v[0:1], v[4:5]
	v_pk_mul_f32 v[16:17], v[10:11], v[10:11]
	v_pk_mul_f32 v[4:5], v[0:1], v[0:1]
	v_pk_mul_f32 v[2:3], v[2:3], v[6:7]
	v_add_f32_e32 v4, v4, v5
	v_add_f32_e32 v4, v16, v4
	v_pk_mul_f32 v[6:7], v[2:3], v[2:3]
	v_add_f32_e32 v4, v17, v4
	v_pk_mul_f32 v[18:19], v[18:19], v[48:49]
	v_add_f32_e32 v4, v6, v4
	v_pk_mul_f32 v[48:49], v[18:19], v[18:19]
	v_add_f32_e32 v4, v7, v4
	v_add_f32_e32 v4, v48, v4
	v_add_f32_e32 v4, v49, v4
	ds_bpermute_b32 v5, v23, v4
	v_bfe_u32 v8, v38, 4, 4
	s_waitcnt lgkmcnt(0)
	v_add_f32_e32 v4, v4, v5
	ds_bpermute_b32 v5, v109, v4
	s_waitcnt lgkmcnt(0)
	v_add_f32_e32 v4, v4, v5
	ds_bpermute_b32 v5, v110, v4
	s_waitcnt lgkmcnt(0)
	v_add_f32_e32 v4, v4, v5
	ds_bpermute_b32 v5, v111, v4
	s_waitcnt lgkmcnt(0)
	v_add_f32_e32 v4, v4, v5
	v_add_f32_e32 v4, 0x358637bd, v4
	v_cmp_gt_f32_e32 vcc, s70, v4
	v_mul_f32_e32 v5, 0x4b800000, v4
	s_nop 0
	v_cndmask_b32_e32 v4, v4, v5, vcc
	v_rsq_f32_e32 v4, v4
	s_nop 0
	v_mul_f32_e32 v5, 0x45800000, v4
	v_cndmask_b32_e32 v4, v4, v5, vcc
	v_pk_mul_f32 v[0:1], v[0:1], v[4:5] op_sel_hi:[1,0]
	v_pk_mul_f32 v[6:7], v[10:11], v[4:5] op_sel_hi:[1,0]
	v_pk_mul_f32 v[2:3], v[2:3], v[4:5] op_sel_hi:[1,0]
	v_pk_mul_f32 v[4:5], v[18:19], v[4:5] op_sel_hi:[1,0]
	v_cvt_pk_bf16_f32 v0, v0, v1
	v_cvt_pk_bf16_f32 v1, v6, v7
	v_cvt_pk_bf16_f32 v2, v2, v3
	v_cvt_pk_bf16_f32 v3, v4, v5
	ds_write_b128 v25, v[0:3] offset:25856
	v_or_b32_e32 v25, 48, v8
	ds_read_b128 v[16:19], v108 offset:512
	ds_read_b128 v[42:45], v108 offset:528
	ds_read_b128 v[112:115], v108 offset:1536
	ds_read_b128 v[118:121], v108 offset:1552
	ds_read_b128 v[122:125], v108 offset:2560
	ds_read_b128 v[128:131], v108 offset:2576
	ds_read_b128 v[132:135], v108 offset:3584
	ds_read_b128 v[144:147], v108 offset:3600
	s_waitcnt vmcnt(3)
	v_lshlrev_b32_e32 v48, 16, v229
	v_and_b32_e32 v49, 0xffff0000, v229
	s_waitcnt lgkmcnt(6)
	v_pk_fma_f32 v[44:45], v[44:45], v[48:49], 0 op_sel_hi:[1,1,0]
	s_waitcnt vmcnt(2)
	v_lshlrev_b32_e32 v48, 16, v233
	v_and_b32_e32 v49, 0xffff0000, v233
	s_waitcnt lgkmcnt(4)
	v_pk_fma_f32 v[44:45], v[120:121], v[48:49], v[44:45]
	v_lshlrev_b32_e32 v120, 16, v228
	s_waitcnt vmcnt(1)
	v_lshlrev_b32_e32 v48, 16, v237
	v_and_b32_e32 v49, 0xffff0000, v237
	s_waitcnt lgkmcnt(2)
	v_pk_fma_f32 v[44:45], v[130:131], v[48:49], v[44:45]
	s_waitcnt vmcnt(0)
	v_lshlrev_b32_e32 v48, 16, v241
	v_and_b32_e32 v49, 0xffff0000, v241
	s_waitcnt lgkmcnt(0)
	v_pk_fma_f32 v[44:45], v[146:147], v[48:49], v[44:45]
	v_and_b32_e32 v121, 0xffff0000, v228
	v_mul_f32_e32 v3, 0xbfb8aa3b, v44
	v_exp_f32_e32 v3, v3
	v_and_b32_e32 v7, 0xffff0000, v236
	v_and_b32_e32 v11, 0xffff0000, v227
	v_and_b32_e32 v15, 0xffff0000, v231
	v_add_f32_e32 v3, 1.0, v3
	v_rcp_f32_e32 v48, v3
	v_mul_f32_e32 v3, 0xbfb8aa3b, v45
	v_exp_f32_e32 v3, v3
	s_nop 0
	v_add_f32_e32 v3, 1.0, v3
	v_rcp_f32_e32 v49, v3
	v_pk_fma_f32 v[2:3], v[42:43], v[120:121], 0 op_sel_hi:[1,1,0]
	v_lshlrev_b32_e32 v42, 16, v232
	v_and_b32_e32 v43, 0xffff0000, v232
	v_pk_fma_f32 v[2:3], v[118:119], v[42:43], v[2:3]
	v_lshlrev_b32_e32 v6, 16, v236
	v_lshlrev_b32_e32 v10, 16, v227
	v_pk_fma_f32 v[2:3], v[128:129], v[6:7], v[2:3]
	v_lshlrev_b32_e32 v6, 16, v240
	v_and_b32_e32 v7, 0xffff0000, v240
	v_pk_fma_f32 v[10:11], v[18:19], v[10:11], 0 op_sel_hi:[1,1,0]
	v_lshlrev_b32_e32 v14, 16, v231
	v_pk_fma_f32 v[10:11], v[114:115], v[14:15], v[10:11]
	v_lshlrev_b32_e32 v14, 16, v235
	v_and_b32_e32 v15, 0xffff0000, v235
	v_pk_fma_f32 v[10:11], v[124:125], v[14:15], v[10:11]
	v_lshlrev_b32_e32 v14, 16, v239
	v_and_b32_e32 v15, 0xffff0000, v239
	v_pk_fma_f32 v[10:11], v[134:135], v[14:15], v[10:11]
	v_lshlrev_b32_e32 v18, 16, v226
	v_mul_f32_e32 v1, 0xbfb8aa3b, v10
	v_exp_f32_e32 v1, v1
	v_and_b32_e32 v19, 0xffff0000, v226
	v_and_b32_e32 v5, 0xffff0000, v234
	v_pk_fma_f32 v[2:3], v[144:145], v[6:7], v[2:3]
	v_add_f32_e32 v1, 1.0, v1
	v_rcp_f32_e32 v14, v1
	v_mul_f32_e32 v1, 0xbfb8aa3b, v11
	v_exp_f32_e32 v1, v1
	v_mul_f32_e32 v6, 0xbfb8aa3b, v2
	v_mul_f32_e32 v7, 0xbfb8aa3b, v3
	v_exp_f32_e32 v6, v6
	v_add_f32_e32 v1, 1.0, v1
	v_rcp_f32_e32 v15, v1
	v_pk_fma_f32 v[0:1], v[16:17], v[18:19], 0 op_sel_hi:[1,1,0]
	v_lshlrev_b32_e32 v16, 16, v230
	v_and_b32_e32 v17, 0xffff0000, v230
	v_pk_fma_f32 v[0:1], v[112:113], v[16:17], v[0:1]
	v_lshlrev_b32_e32 v4, 16, v234
	v_pk_fma_f32 v[0:1], v[122:123], v[4:5], v[0:1]
	v_lshlrev_b32_e32 v4, 16, v238
	v_and_b32_e32 v5, 0xffff0000, v238
	v_pk_fma_f32 v[0:1], v[132:133], v[4:5], v[0:1]
	v_exp_f32_e32 v7, v7
	v_mul_f32_e32 v4, 0xbfb8aa3b, v0
	v_mul_f32_e32 v5, 0xbfb8aa3b, v1
	v_exp_f32_e32 v4, v4
	v_exp_f32_e32 v5, v5
	v_add_f32_e32 v6, 1.0, v6
	v_add_f32_e32 v7, 1.0, v7
	v_add_f32_e32 v4, 1.0, v4
	v_add_f32_e32 v5, 1.0, v5
	v_rcp_f32_e32 v4, v4
	v_rcp_f32_e32 v5, v5
	v_rcp_f32_e32 v6, v6
	v_rcp_f32_e32 v7, v7
	v_pk_mul_f32 v[10:11], v[10:11], v[14:15]
	v_pk_mul_f32 v[0:1], v[0:1], v[4:5]
	v_pk_mul_f32 v[14:15], v[10:11], v[10:11]
	v_pk_mul_f32 v[4:5], v[0:1], v[0:1]
	v_pk_mul_f32 v[2:3], v[2:3], v[6:7]
	v_add_f32_e32 v4, v4, v5
	v_add_f32_e32 v4, v14, v4
	v_pk_mul_f32 v[6:7], v[2:3], v[2:3]
	v_add_f32_e32 v4, v15, v4
	v_pk_mul_f32 v[44:45], v[44:45], v[48:49]
	v_add_f32_e32 v4, v6, v4
	v_pk_mul_f32 v[48:49], v[44:45], v[44:45]
	v_add_f32_e32 v4, v7, v4
	v_add_f32_e32 v4, v48, v4
	v_add_f32_e32 v4, v49, v4
	ds_bpermute_b32 v5, v23, v4
	v_lshlrev_b32_e32 v16, 5, v40
	s_waitcnt lgkmcnt(0)
	v_add_f32_e32 v4, v4, v5
	ds_bpermute_b32 v5, v109, v4
	s_waitcnt lgkmcnt(0)
	v_add_f32_e32 v4, v4, v5
	ds_bpermute_b32 v5, v110, v4
	s_waitcnt lgkmcnt(0)
	v_add_f32_e32 v4, v4, v5
	ds_bpermute_b32 v5, v111, v4
	s_waitcnt lgkmcnt(0)
	v_add_f32_e32 v4, v4, v5
	v_add_f32_e32 v4, 0x358637bd, v4
	v_cmp_gt_f32_e32 vcc, s70, v4
	v_mul_f32_e32 v5, 0x4b800000, v4
	s_nop 0
	v_cndmask_b32_e32 v4, v4, v5, vcc
	v_rsq_f32_e32 v4, v4
	s_nop 0
	v_mul_f32_e32 v5, 0x45800000, v4
	v_cndmask_b32_e32 v4, v4, v5, vcc
	v_pk_mul_f32 v[0:1], v[0:1], v[4:5] op_sel_hi:[1,0]
	v_pk_mul_f32 v[6:7], v[10:11], v[4:5] op_sel_hi:[1,0]
	v_pk_mul_f32 v[2:3], v[2:3], v[4:5] op_sel_hi:[1,0]
	v_pk_mul_f32 v[4:5], v[44:45], v[4:5] op_sel_hi:[1,0]
	v_cvt_pk_bf16_f32 v2, v2, v3
	v_cvt_pk_bf16_f32 v3, v4, v5
	v_mul_u32_u24_e32 v4, 0x110, v25
	v_cvt_pk_bf16_f32 v0, v0, v1
	v_cvt_pk_bf16_f32 v1, v6, v7
	v_add3_u32 v4, v196, v4, v26
	ds_write_b128 v4, v[0:3] offset:21504
	v_cmp_lt_u32_e32 vcc, 1, v20
	v_add_u32_e32 v2, 0x5400, v196
	s_and_saveexec_b64 s[0:1], vcc
	s_xor_b64 s[0:1], exec, s[0:1]
	v_add_u32_e32 v2, 0x1000, v196
	v_lshlrev_b32_e32 v16, 5, v40
	s_or_saveexec_b64 s[0:1], s[0:1]
	v_mov_b32_e32 v23, v37
	v_and_b32_e32 v14, 63, v38
	v_add_u32_e32 v15, 0x11800, v196
	v_add_u32_e32 v12, 0x11c00, v196
	v_add_u32_e32 v13, 0x11a00, v196
	v_mov_b32_e32 v0, 0xc800
	s_xor_b64 exec, exec, s[0:1]
	s_cbranch_execz .LBB0_293
	v_or_b32_e32 v3, v107, v20
	v_lshlrev_b32_e32 v20, 16, v3
	v_lshl_add_u64 v[0:1], s[16:17], 0, v[20:21]
	v_lshlrev_b64 v[4:5], 2, v[22:23]
	v_lshl_add_u64 v[6:7], v[0:1], 0, v[4:5]
	v_lshl_add_u64 v[4:5], s[16:17], 0, v[4:5]
	v_lshlrev_b32_e32 v0, 2, v14
	v_mov_b32_e32 v1, v21
	v_lshl_add_u64 v[4:5], v[4:5], 0, v[20:21]
	v_lshl_add_u64 v[4:5], v[4:5], 0, v[0:1]
	v_add_co_u32_e32 v4, vcc, 0x200000, v4
	v_lshl_add_u64 v[6:7], v[6:7], 0, v[0:1]
	s_nop 0
	v_addc_co_u32_e32 v5, vcc, 0, v5, vcc
	v_readlane_b32 s36, v250, 19
	global_load_dword v7, v[6:7], off
	v_readlane_b32 s37, v250, 20
	global_load_dword v4, v[4:5], off
	v_lshlrev_b32_e32 v6, 2, v3
	s_mov_b32 s2, 0xbfb8aa3b
	v_readlane_b32 s38, v250, 21
	v_readlane_b32 s39, v250, 22
	global_load_dword v5, v6, s[36:37]
	v_readlane_b32 s40, v250, 23
	v_readlane_b32 s41, v250, 24
	v_readlane_b32 s42, v250, 25
	v_readlane_b32 s43, v250, 26
	v_readlane_b32 s44, v250, 27
	v_readlane_b32 s45, v250, 28
	v_readlane_b32 s46, v250, 29
	v_readlane_b32 s47, v250, 30
	v_readlane_b32 s48, v250, 31
	v_readlane_b32 s49, v250, 32
	v_readlane_b32 s50, v250, 33
	v_readlane_b32 s51, v250, 34
	v_readlane_b32 s36, v250, 3
	v_readlane_b32 s50, v250, 17
	v_readlane_b32 s51, v250, 18
	v_readlane_b32 s4, v250, 41
	v_readlane_b32 s5, v250, 42
	v_readlane_b32 s37, v250, 4
	v_readlane_b32 s38, v250, 5
	v_readlane_b32 s39, v250, 6
	global_load_dword v6, v6, s[50:51]
	v_readlane_b32 s40, v250, 7
	v_readlane_b32 s41, v250, 8
	v_readlane_b32 s42, v250, 9
	v_readlane_b32 s43, v250, 10
	v_readlane_b32 s44, v250, 11
	v_readlane_b32 s45, v250, 12
	v_readlane_b32 s46, v250, 13
	v_readlane_b32 s47, v250, 14
	v_readlane_b32 s48, v250, 15
	v_readlane_b32 s49, v250, 16
	s_waitcnt vmcnt(2)
	v_mul_f32_e32 v4, 0xbfb8aa3b, v4
	v_exp_f32_e32 v4, v4
	s_waitcnt vmcnt(1)
	v_add_f32_e32 v5, v7, v5
	v_mul_f32_e64 v8, |v5|, s2
	v_fma_f32 v9, |v5|, s2, -v8
	s_mov_b32 s2, 0xb2a5705f
	v_rndne_f32_e32 v10, v8
	v_fma_f32 v9, |v5|, s2, v9
	v_sub_f32_e32 v8, v8, v10
	v_add_f32_e32 v8, v8, v9
	v_exp_f32_e32 v8, v8
	v_cvt_i32_f32_e32 v9, v10
	s_mov_b32 s2, 0x42ce8ed0
	v_cmp_ngt_f32_e64 vcc, |v5|, s2
	s_mov_b32 s2, 0xc2b17218
	v_ldexp_f32 v8, v8, v9
	v_cndmask_b32_e32 v8, 0, v8, vcc
	v_cmp_nlt_f32_e64 vcc, |v5|, s2
	v_max_f32_e32 v7, 0, v5
	s_mov_b32 s2, 0x3f2aaaab
	v_cndmask_b32_e32 v5, v193, v8, vcc
	v_add_f32_e32 v10, 1.0, v5
	v_add_f32_e32 v8, -1.0, v10
	v_sub_f32_e32 v9, v8, v10
	v_add_f32_e32 v9, 1.0, v9
	v_sub_f32_e32 v8, v5, v8
	v_add_f32_e32 v11, v8, v9
	v_frexp_mant_f32_e32 v8, v10
	v_cmp_gt_f32_e32 vcc, s2, v8
	v_cvt_f64_f32_e32 v[8:9], v10
	v_frexp_exp_i32_f64_e32 v8, v[8:9]
	v_subbrev_co_u32_e32 v8, vcc, 0, v8, vcc
	v_sub_u32_e32 v9, 0, v8
	v_ldexp_f32 v10, v10, v9
	v_ldexp_f32 v9, v11, v9
	v_add_f32_e32 v11, -1.0, v10
	v_add_f32_e32 v17, 1.0, v11
	v_sub_f32_e32 v17, v10, v17
	v_add_f32_e32 v17, v9, v17
	v_add_f32_e32 v18, v11, v17
	v_sub_f32_e32 v11, v11, v18
	v_add_f32_e32 v11, v17, v11
	v_add_f32_e32 v17, 1.0, v10
	v_add_f32_e32 v19, -1.0, v17
	v_sub_f32_e32 v10, v10, v19
	v_add_f32_e32 v9, v9, v10
	v_add_f32_e32 v10, v17, v9
	v_sub_f32_e32 v17, v17, v10
	v_add_f32_e32 v9, v9, v17
	v_rcp_f32_e32 v17, v10
	v_cvt_f32_i32_e32 v8, v8
	s_mov_b32 s2, 0x3f317218
	v_add_f32_e32 v4, 1.0, v4
	v_mul_f32_e32 v19, v18, v17
	v_mul_f32_e32 v20, v10, v19
	v_fma_f32 v25, v19, v10, -v20
	v_fmac_f32_e32 v25, v19, v9
	v_add_f32_e32 v36, v20, v25
	v_sub_f32_e32 v40, v18, v36
	v_sub_f32_e32 v18, v18, v40
	v_sub_f32_e32 v20, v36, v20
	v_sub_f32_e32 v18, v18, v36
	v_add_f32_e32 v11, v11, v18
	v_sub_f32_e32 v18, v20, v25
	v_add_f32_e32 v11, v18, v11
	v_add_f32_e32 v18, v40, v11
	v_mul_f32_e32 v20, v17, v18
	v_mul_f32_e32 v25, v10, v20
	v_fma_f32 v10, v20, v10, -v25
	v_fmac_f32_e32 v10, v20, v9
	v_sub_f32_e32 v9, v40, v18
	v_add_f32_e32 v9, v11, v9
	v_add_f32_e32 v11, v25, v10
	v_sub_f32_e32 v36, v18, v11
	v_sub_f32_e32 v18, v18, v36
	v_sub_f32_e32 v25, v11, v25
	v_sub_f32_e32 v11, v18, v11
	v_add_f32_e32 v9, v9, v11
	v_sub_f32_e32 v10, v25, v10
	v_add_f32_e32 v9, v10, v9
	v_add_f32_e32 v10, v19, v20
	v_add_f32_e32 v9, v36, v9
	v_sub_f32_e32 v11, v10, v19
	v_mul_f32_e32 v9, v17, v9
	v_sub_f32_e32 v11, v20, v11
	v_add_f32_e32 v9, v11, v9
	v_mul_f32_e32 v19, 0x3f317218, v8
	v_add_f32_e32 v11, v10, v9
	v_fma_f32 v20, v8, s2, -v19
	v_mul_f32_e32 v17, v11, v11
	v_fmac_f32_e32 v20, 0xb102e308, v8
	v_sub_f32_e32 v8, v11, v10
	v_fmamk_f32 v18, v17, 0x3e9b6dac, v188
	v_sub_f32_e32 v8, v9, v8
	v_add_f32_e32 v9, v19, v20
	v_fmaak_f32 v18, v17, v18, 0x3f2aaada
	v_sub_f32_e32 v10, v9, v19
	v_ldexp_f32 v19, v11, 1
	v_mul_f32_e32 v11, v11, v17
	v_mul_f32_e32 v11, v11, v18
	v_add_f32_e32 v17, v19, v11
	v_sub_f32_e32 v18, v17, v19
	v_ldexp_f32 v8, v8, 1
	v_sub_f32_e32 v11, v11, v18
	v_add_f32_e32 v8, v8, v11
	v_add_f32_e32 v11, v17, v8
	v_sub_f32_e32 v17, v11, v17
	v_sub_f32_e32 v8, v8, v17
	v_add_f32_e32 v17, v9, v11
	v_sub_f32_e32 v18, v17, v9
	v_sub_f32_e32 v19, v17, v18
	v_sub_f32_e32 v10, v20, v10
	v_sub_f32_e32 v9, v9, v19
	v_sub_f32_e32 v11, v11, v18
	v_add_f32_e32 v9, v11, v9
	v_add_f32_e32 v11, v10, v8
	v_sub_f32_e32 v18, v11, v10
	v_sub_f32_e32 v19, v11, v18
	v_sub_f32_e32 v10, v10, v19
	v_sub_f32_e32 v8, v8, v18
	v_add_f32_e32 v9, v11, v9
	v_add_f32_e32 v8, v8, v10
	v_add_f32_e32 v10, v17, v9
	v_sub_f32_e32 v11, v10, v17
	v_sub_f32_e32 v9, v9, v11
	v_add_f32_e32 v8, v8, v9
	s_mov_b32 s2, 0x7f800000
	v_add_f32_e32 v8, v10, v8
	v_cmp_neq_f32_e32 vcc, s2, v5
	s_mov_b32 s2, 0x33800000
	v_rcp_f32_e32 v4, v4
	v_cndmask_b32_e32 v8, v193, v8, vcc
	v_cmp_lt_f32_e64 vcc, |v5|, s2
	s_mov_b32 s2, 0x3fb8aa3b
	v_lshlrev_b32_e32 v20, 2, v39
	v_cndmask_b32_e32 v5, v8, v5, vcc
	v_add_f32_e32 v5, v7, v5
	s_waitcnt vmcnt(0)
	v_mul_f32_e32 v7, 0x3fb8aa3b, v6
	v_fma_f32 v8, v6, s2, -v7
	v_rndne_f32_e32 v9, v7
	v_fmac_f32_e32 v8, 0x32a5705f, v6
	v_sub_f32_e32 v7, v7, v9
	v_add_f32_e32 v7, v7, v8
	v_exp_f32_e32 v7, v7
	v_cvt_i32_f32_e32 v8, v9
	s_mov_b32 s2, 0xc2ce8ed0
	v_cmp_ngt_f32_e32 vcc, s2, v6
	s_mov_b32 s2, 0x42b17218
	v_ldexp_f32 v7, v7, v8
	v_cndmask_b32_e32 v7, 0, v7, vcc
	v_cmp_nlt_f32_e32 vcc, s2, v6
	v_add_u32_e32 v8, -1, v191
	s_nop 0
	v_cndmask_b32_e32 v7, v193, v7, vcc
	v_cmp_lt_i32_e32 vcc, v8, v47
	v_mul_f32_e64 v6, v5, -v7
	s_nop 0
	v_cndmask_b32_e32 v8, v8, v191, vcc
	v_lshlrev_b32_e32 v8, 2, v8
	ds_bpermute_b32 v8, v8, v6
	v_cmp_eq_u32_e32 vcc, 0, v14
	s_waitcnt lgkmcnt(0)
	v_fma_f32 v5, v5, -v7, v8
	v_cndmask_b32_e32 v5, v5, v6, vcc
	v_add_u32_e32 v6, -2, v191
	v_cmp_lt_i32_e32 vcc, v6, v47
	s_nop 1
	v_cndmask_b32_e32 v6, v6, v191, vcc
	v_lshlrev_b32_e32 v6, 2, v6
	ds_bpermute_b32 v6, v6, v5
	v_cmp_gt_u32_e32 vcc, 2, v14
	s_waitcnt lgkmcnt(0)
	v_add_f32_e32 v6, v5, v6
	v_cndmask_b32_e32 v5, v6, v5, vcc
	v_add_u32_e32 v6, -4, v191
	v_cmp_lt_i32_e32 vcc, v6, v47
	s_nop 1
	v_cndmask_b32_e32 v6, v6, v191, vcc
	v_lshlrev_b32_e32 v6, 2, v6
	ds_bpermute_b32 v6, v6, v5
	v_cmp_gt_u32_e32 vcc, 4, v14
	s_waitcnt lgkmcnt(0)
	v_add_f32_e32 v6, v5, v6
	v_cndmask_b32_e32 v5, v6, v5, vcc
	v_add_u32_e32 v6, -8, v191
	v_cmp_lt_i32_e32 vcc, v6, v47
	s_nop 1
	v_cndmask_b32_e32 v6, v6, v191, vcc
	v_lshlrev_b32_e32 v6, 2, v6
	ds_bpermute_b32 v6, v6, v5
	v_cmp_gt_u32_e32 vcc, 8, v14
	s_waitcnt lgkmcnt(0)
	v_add_f32_e32 v6, v5, v6
	v_cndmask_b32_e32 v5, v6, v5, vcc
	v_add_u32_e32 v6, -16, v191
	v_cmp_lt_i32_e32 vcc, v6, v47
	s_nop 1
	v_cndmask_b32_e32 v6, v6, v191, vcc
	v_lshlrev_b32_e32 v6, 2, v6
	ds_bpermute_b32 v6, v6, v5
	v_cmp_gt_u32_e32 vcc, 16, v14
	s_waitcnt lgkmcnt(0)
	v_add_f32_e32 v6, v5, v6
	v_cndmask_b32_e32 v5, v6, v5, vcc
	v_subrev_u32_e32 v6, 32, v191
	v_cmp_lt_i32_e32 vcc, v6, v47
	s_nop 1
	v_cndmask_b32_e32 v6, v6, v191, vcc
	v_lshlrev_b32_e32 v6, 2, v6
	ds_bpermute_b32 v6, v6, v5
	v_cmp_gt_u32_e32 vcc, 32, v14
	s_waitcnt lgkmcnt(0)
	v_add_f32_e32 v6, v5, v6
	v_cndmask_b32_e32 v6, v6, v5, vcc
	v_lshlrev_b32_e32 v5, 2, v194
	v_add_u32_e32 v7, v15, v5
	ds_write_b32 v7, v6
	v_add_u32_e32 v7, v13, v5
	ds_write_b32 v7, v4
	v_mul_f32_e32 v7, 0x3fb8aa3b, v6
	v_exp_f32_e32 v7, v7
	v_add_u32_e32 v5, v12, v5
	v_mul_f32_e32 v4, v4, v7
	ds_write_b32 v5, v4
	v_or_b32_e32 v4, v3, v16
	v_ashrrev_i32_e32 v5, 31, v4
	v_lshlrev_b64 v[4:5], 15, v[4:5]
	v_lshl_add_u64 v[4:5], s[4:5], 0, v[4:5]
	v_lshl_add_u64 v[4:5], v[4:5], 0, v[20:21]
	v_lshl_add_u64 v[0:1], v[4:5], 0, v[0:1]
	global_store_dword v[0:1], v6, off
	v_mov_b32_e32 v0, 0x8800
